# v87 plus non-temporal hint on the write-once hidden-activation and GIN output stores of the MLP1A/MLP1B/GIN hand tiles
# baseline (speedup 1.0000x reference)
.Lt_mlp1b:
	v_add_u32_e32 v169, s32, v164
	v_mfma_f32_16x16x32_f16 v[4:7], v[132:135], v[184:187], v[4:7]
	ds_read_b128 v[238:241], v169 offset:4112
	v_mfma_f32_16x16x32_f16 v[8:11], v[136:139], v[184:187], v[8:11]
	ds_read_b128 v[242:245], v169 offset:5136
	v_mfma_f32_16x16x32_f16 v[12:15], v[140:143], v[184:187], v[12:15]
	ds_read_b128 v[246:249], v169 offset:6160
	v_mfma_f32_16x16x32_f16 v[16:19], v[144:147], v[184:187], v[16:19]
	ds_read_b128 v[250:253], v169 offset:7184
	v_mfma_f32_16x16x32_f16 v[20:23], v[132:135], v[188:191], v[20:23]
	v_mfma_f32_16x16x32_f16 v[24:27], v[136:139], v[188:191], v[24:27]
	v_mfma_f32_16x16x32_f16 v[28:31], v[140:143], v[188:191], v[28:31]
	v_mfma_f32_16x16x32_f16 v[32:35], v[144:147], v[188:191], v[32:35]
	v_mfma_f32_16x16x32_f16 v[36:39], v[132:135], v[192:195], v[36:39]
	v_mfma_f32_16x16x32_f16 v[40:43], v[136:139], v[192:195], v[40:43]
	v_mfma_f32_16x16x32_f16 v[44:47], v[140:143], v[192:195], v[44:47]
	v_mfma_f32_16x16x32_f16 v[48:51], v[144:147], v[192:195], v[48:51]
	v_mfma_f32_16x16x32_f16 v[52:55], v[132:135], v[196:199], v[52:55]
	v_mfma_f32_16x16x32_f16 v[56:59], v[136:139], v[196:199], v[56:59]
	v_mfma_f32_16x16x32_f16 v[60:63], v[140:143], v[196:199], v[60:63]
	v_mfma_f32_16x16x32_f16 v[64:67], v[144:147], v[196:199], v[64:67]
	s_waitcnt vmcnt(8) lgkmcnt(0)
	s_barrier
	s_add_i32 s37, s32, 0x8000
	s_cmp_lg_u32 s32, 0x18000
	s_cselect_b32 s37, s37, 0
	v_add_u32_e32 v168, s37, v165
	v_add_u32_e32 v169, s37, v164
	s_add_u32 vcc_lo, s24, s32
	v_mfma_f32_16x16x32_f16 v[68:71], v[132:135], v[238:241], v[68:71]
	ds_read_b128 v[148:151], v168 offset:16
	ds_read_b128 v[184:187], v169 offset:16
	v_mfma_f32_16x16x32_f16 v[72:75], v[136:139], v[238:241], v[72:75]
	ds_read_b128 v[152:155], v168 offset:1040
	ds_read_b128 v[188:191], v169 offset:1040
	v_mfma_f32_16x16x32_f16 v[76:79], v[140:143], v[238:241], v[76:79]
	ds_read_b128 v[156:159], v168 offset:2064
	ds_read_b128 v[192:195], v169 offset:2064
	v_mfma_f32_16x16x32_f16 v[80:83], v[144:147], v[238:241], v[80:83]
	ds_read_b128 v[160:163], v168 offset:3088
	ds_read_b128 v[196:199], v169 offset:3088
	v_mfma_f32_16x16x32_f16 v[84:87], v[132:135], v[242:245], v[84:87]
	v_mfma_f32_16x16x32_f16 v[88:91], v[136:139], v[242:245], v[88:91]
	v_mfma_f32_16x16x32_f16 v[92:95], v[140:143], v[242:245], v[92:95]
	v_mfma_f32_16x16x32_f16 v[96:99], v[144:147], v[242:245], v[96:99]
	v_mfma_f32_16x16x32_f16 v[100:103], v[132:135], v[246:249], v[100:103]
	s_mov_b32 m0, vcc_lo
	s_nop 0
	global_load_lds_dwordx4 v170, s[30:31]
	v_mfma_f32_16x16x32_f16 v[104:107], v[136:139], v[246:249], v[104:107]
	s_add_u32 m0, vcc_lo, 0x400
	s_nop 0
	global_load_lds_dwordx4 v171, s[30:31]
	v_mfma_f32_16x16x32_f16 v[108:111], v[140:143], v[246:249], v[108:111]
	s_add_u32 m0, vcc_lo, 0x4000
	s_nop 0
	global_load_lds_dwordx4 v170, s[52:53]
	v_mfma_f32_16x16x32_f16 v[112:115], v[144:147], v[246:249], v[112:115]
	s_add_u32 m0, vcc_lo, 0x4400
	s_nop 0
	global_load_lds_dwordx4 v171, s[52:53]
	v_mfma_f32_16x16x32_f16 v[116:119], v[132:135], v[250:253], v[116:119]
	v_mfma_f32_16x16x32_f16 v[120:123], v[136:139], v[250:253], v[120:123]
	v_mfma_f32_16x16x32_f16 v[124:127], v[140:143], v[250:253], v[124:127]
	v_mfma_f32_16x16x32_f16 v[128:131], v[144:147], v[250:253], v[128:131]
	s_waitcnt lgkmcnt(0)
	s_mov_b32 s32, s37
	s_add_u32 s30, s30, 64
	s_addc_u32 s31, s31, 0
	s_add_u32 s52, s52, 64
	s_addc_u32 s53, s53, 0
	v_add_u32_e32 v169, s32, v164
	v_mfma_f32_16x16x32_f16 v[4:7], v[148:151], v[184:187], v[4:7]
	ds_read_b128 v[238:241], v169 offset:4112
	v_mfma_f32_16x16x32_f16 v[8:11], v[152:155], v[184:187], v[8:11]
	ds_read_b128 v[242:245], v169 offset:5136
	v_mfma_f32_16x16x32_f16 v[12:15], v[156:159], v[184:187], v[12:15]
	ds_read_b128 v[246:249], v169 offset:6160
	v_mfma_f32_16x16x32_f16 v[16:19], v[160:163], v[184:187], v[16:19]
	ds_read_b128 v[250:253], v169 offset:7184
	v_mfma_f32_16x16x32_f16 v[20:23], v[148:151], v[188:191], v[20:23]
	v_mfma_f32_16x16x32_f16 v[24:27], v[152:155], v[188:191], v[24:27]
	v_mfma_f32_16x16x32_f16 v[28:31], v[156:159], v[188:191], v[28:31]
	v_mfma_f32_16x16x32_f16 v[32:35], v[160:163], v[188:191], v[32:35]
	v_mfma_f32_16x16x32_f16 v[36:39], v[148:151], v[192:195], v[36:39]
	v_mfma_f32_16x16x32_f16 v[40:43], v[152:155], v[192:195], v[40:43]
	v_mfma_f32_16x16x32_f16 v[44:47], v[156:159], v[192:195], v[44:47]
	v_mfma_f32_16x16x32_f16 v[48:51], v[160:163], v[192:195], v[48:51]
	v_mfma_f32_16x16x32_f16 v[52:55], v[148:151], v[196:199], v[52:55]
	v_mfma_f32_16x16x32_f16 v[56:59], v[152:155], v[196:199], v[56:59]
	v_mfma_f32_16x16x32_f16 v[60:63], v[156:159], v[196:199], v[60:63]
	v_mfma_f32_16x16x32_f16 v[64:67], v[160:163], v[196:199], v[64:67]
	s_waitcnt vmcnt(8) lgkmcnt(0)
	s_barrier
	s_add_i32 s37, s32, 0x8000
	s_cmp_lg_u32 s32, 0x18000
	s_cselect_b32 s37, s37, 0
	v_add_u32_e32 v168, s37, v165
	v_add_u32_e32 v169, s37, v164
	s_add_u32 vcc_lo, s24, s32
	v_mfma_f32_16x16x32_f16 v[68:71], v[148:151], v[238:241], v[68:71]
	ds_read_b128 v[132:135], v168 offset:16
	ds_read_b128 v[184:187], v169 offset:16
	v_mfma_f32_16x16x32_f16 v[72:75], v[152:155], v[238:241], v[72:75]
	ds_read_b128 v[136:139], v168 offset:1040
	ds_read_b128 v[188:191], v169 offset:1040
	v_mfma_f32_16x16x32_f16 v[76:79], v[156:159], v[238:241], v[76:79]
	ds_read_b128 v[140:143], v168 offset:2064
	ds_read_b128 v[192:195], v169 offset:2064
	v_mfma_f32_16x16x32_f16 v[80:83], v[160:163], v[238:241], v[80:83]
	ds_read_b128 v[144:147], v168 offset:3088
	ds_read_b128 v[196:199], v169 offset:3088
	v_mfma_f32_16x16x32_f16 v[84:87], v[148:151], v[242:245], v[84:87]
	v_mfma_f32_16x16x32_f16 v[88:91], v[152:155], v[242:245], v[88:91]
	v_mfma_f32_16x16x32_f16 v[92:95], v[156:159], v[242:245], v[92:95]
	v_mfma_f32_16x16x32_f16 v[96:99], v[160:163], v[242:245], v[96:99]
	v_mfma_f32_16x16x32_f16 v[100:103], v[148:151], v[246:249], v[100:103]
	s_mov_b32 m0, vcc_lo
	s_nop 0
	global_load_lds_dwordx4 v170, s[30:31]
	v_mfma_f32_16x16x32_f16 v[104:107], v[152:155], v[246:249], v[104:107]
	s_add_u32 m0, vcc_lo, 0x400
	s_nop 0
	global_load_lds_dwordx4 v171, s[30:31]
	v_mfma_f32_16x16x32_f16 v[108:111], v[156:159], v[246:249], v[108:111]
	s_add_u32 m0, vcc_lo, 0x4000
	s_nop 0
	global_load_lds_dwordx4 v170, s[52:53]
	v_mfma_f32_16x16x32_f16 v[112:115], v[160:163], v[246:249], v[112:115]
	s_add_u32 m0, vcc_lo, 0x4400
	s_nop 0
	global_load_lds_dwordx4 v171, s[52:53]
	v_mfma_f32_16x16x32_f16 v[116:119], v[148:151], v[250:253], v[116:119]
	v_mfma_f32_16x16x32_f16 v[120:123], v[152:155], v[250:253], v[120:123]
	v_mfma_f32_16x16x32_f16 v[124:127], v[156:159], v[250:253], v[124:127]
	v_mfma_f32_16x16x32_f16 v[128:131], v[160:163], v[250:253], v[128:131]
	s_waitcnt lgkmcnt(0)
	s_mov_b32 s32, s37
	s_add_u32 s30, s30, 64
	s_addc_u32 s31, s31, 0
	s_add_u32 s52, s52, 64
	s_addc_u32 s53, s53, 0
	s_add_i32 s57, s57, 2
	s_cmp_lt_u32 s57, 28
	s_cbranch_scc1 .Lt_mlp1b
	v_add_u32_e32 v169, s32, v164
	v_mfma_f32_16x16x32_f16 v[4:7], v[132:135], v[184:187], v[4:7]
	ds_read_b128 v[238:241], v169 offset:4112
	v_mfma_f32_16x16x32_f16 v[8:11], v[136:139], v[184:187], v[8:11]
	ds_read_b128 v[242:245], v169 offset:5136
	v_mfma_f32_16x16x32_f16 v[12:15], v[140:143], v[184:187], v[12:15]
	ds_read_b128 v[246:249], v169 offset:6160
	v_mfma_f32_16x16x32_f16 v[16:19], v[144:147], v[184:187], v[16:19]
	ds_read_b128 v[250:253], v169 offset:7184
	v_mfma_f32_16x16x32_f16 v[20:23], v[132:135], v[188:191], v[20:23]
	v_mfma_f32_16x16x32_f16 v[24:27], v[136:139], v[188:191], v[24:27]
	v_mfma_f32_16x16x32_f16 v[28:31], v[140:143], v[188:191], v[28:31]
	v_mfma_f32_16x16x32_f16 v[32:35], v[144:147], v[188:191], v[32:35]
	v_mfma_f32_16x16x32_f16 v[36:39], v[132:135], v[192:195], v[36:39]
	v_mfma_f32_16x16x32_f16 v[40:43], v[136:139], v[192:195], v[40:43]
	v_mfma_f32_16x16x32_f16 v[44:47], v[140:143], v[192:195], v[44:47]
	v_mfma_f32_16x16x32_f16 v[48:51], v[144:147], v[192:195], v[48:51]
	v_mfma_f32_16x16x32_f16 v[52:55], v[132:135], v[196:199], v[52:55]
	v_mfma_f32_16x16x32_f16 v[56:59], v[136:139], v[196:199], v[56:59]
	v_mfma_f32_16x16x32_f16 v[60:63], v[140:143], v[196:199], v[60:63]
	v_mfma_f32_16x16x32_f16 v[64:67], v[144:147], v[196:199], v[64:67]
	s_waitcnt vmcnt(8) lgkmcnt(0)
	s_barrier
	s_add_i32 s37, s32, 0x8000
	s_cmp_lg_u32 s32, 0x18000
	s_cselect_b32 s37, s37, 0
	v_add_u32_e32 v168, s37, v165
	v_add_u32_e32 v169, s37, v164
	v_mfma_f32_16x16x32_f16 v[68:71], v[132:135], v[238:241], v[68:71]
	ds_read_b128 v[148:151], v168 offset:16
	ds_read_b128 v[184:187], v169 offset:16
	v_mfma_f32_16x16x32_f16 v[72:75], v[136:139], v[238:241], v[72:75]
	ds_read_b128 v[152:155], v168 offset:1040
	ds_read_b128 v[188:191], v169 offset:1040
	v_mfma_f32_16x16x32_f16 v[76:79], v[140:143], v[238:241], v[76:79]
	ds_read_b128 v[156:159], v168 offset:2064
	ds_read_b128 v[192:195], v169 offset:2064
	v_mfma_f32_16x16x32_f16 v[80:83], v[144:147], v[238:241], v[80:83]
	ds_read_b128 v[160:163], v168 offset:3088
	ds_read_b128 v[196:199], v169 offset:3088
	v_mfma_f32_16x16x32_f16 v[84:87], v[132:135], v[242:245], v[84:87]
	v_mfma_f32_16x16x32_f16 v[88:91], v[136:139], v[242:245], v[88:91]
	v_mfma_f32_16x16x32_f16 v[92:95], v[140:143], v[242:245], v[92:95]
	v_mfma_f32_16x16x32_f16 v[96:99], v[144:147], v[242:245], v[96:99]
	v_mfma_f32_16x16x32_f16 v[100:103], v[132:135], v[246:249], v[100:103]
	v_mfma_f32_16x16x32_f16 v[104:107], v[136:139], v[246:249], v[104:107]
	v_mfma_f32_16x16x32_f16 v[108:111], v[140:143], v[246:249], v[108:111]
	v_mfma_f32_16x16x32_f16 v[112:115], v[144:147], v[246:249], v[112:115]
	v_mfma_f32_16x16x32_f16 v[116:119], v[132:135], v[250:253], v[116:119]
	v_mfma_f32_16x16x32_f16 v[120:123], v[136:139], v[250:253], v[120:123]
	v_mfma_f32_16x16x32_f16 v[124:127], v[140:143], v[250:253], v[124:127]
	v_mfma_f32_16x16x32_f16 v[128:131], v[144:147], v[250:253], v[128:131]
	s_waitcnt lgkmcnt(0)
	s_mov_b32 s32, s37
	v_add_u32_e32 v169, s32, v164
	v_mfma_f32_16x16x32_f16 v[4:7], v[148:151], v[184:187], v[4:7]
	ds_read_b128 v[238:241], v169 offset:4112
	v_mfma_f32_16x16x32_f16 v[8:11], v[152:155], v[184:187], v[8:11]
	ds_read_b128 v[242:245], v169 offset:5136
	v_mfma_f32_16x16x32_f16 v[12:15], v[156:159], v[184:187], v[12:15]
	ds_read_b128 v[246:249], v169 offset:6160
	v_mfma_f32_16x16x32_f16 v[16:19], v[160:163], v[184:187], v[16:19]
	ds_read_b128 v[250:253], v169 offset:7184
	v_mfma_f32_16x16x32_f16 v[20:23], v[148:151], v[188:191], v[20:23]
	v_mfma_f32_16x16x32_f16 v[24:27], v[152:155], v[188:191], v[24:27]
	v_mfma_f32_16x16x32_f16 v[28:31], v[156:159], v[188:191], v[28:31]
	v_mfma_f32_16x16x32_f16 v[32:35], v[160:163], v[188:191], v[32:35]
	v_mfma_f32_16x16x32_f16 v[36:39], v[148:151], v[192:195], v[36:39]
	v_mfma_f32_16x16x32_f16 v[40:43], v[152:155], v[192:195], v[40:43]
	v_mfma_f32_16x16x32_f16 v[44:47], v[156:159], v[192:195], v[44:47]
	v_mfma_f32_16x16x32_f16 v[48:51], v[160:163], v[192:195], v[48:51]
	v_mfma_f32_16x16x32_f16 v[52:55], v[148:151], v[196:199], v[52:55]
	v_mfma_f32_16x16x32_f16 v[56:59], v[152:155], v[196:199], v[56:59]
	v_mfma_f32_16x16x32_f16 v[60:63], v[156:159], v[196:199], v[60:63]
	v_mfma_f32_16x16x32_f16 v[64:67], v[160:163], v[196:199], v[64:67]
	s_waitcnt vmcnt(4) lgkmcnt(0)
	s_barrier
	s_add_i32 s37, s32, 0x8000
	s_cmp_lg_u32 s32, 0x18000
	s_cselect_b32 s37, s37, 0
	v_add_u32_e32 v168, s37, v165
	v_add_u32_e32 v169, s37, v164
	v_mfma_f32_16x16x32_f16 v[68:71], v[148:151], v[238:241], v[68:71]
	ds_read_b128 v[132:135], v168 offset:16
	ds_read_b128 v[184:187], v169 offset:16
	v_mfma_f32_16x16x32_f16 v[72:75], v[152:155], v[238:241], v[72:75]
	ds_read_b128 v[136:139], v168 offset:1040
	ds_read_b128 v[188:191], v169 offset:1040
	v_mfma_f32_16x16x32_f16 v[76:79], v[156:159], v[238:241], v[76:79]
	ds_read_b128 v[140:143], v168 offset:2064
	ds_read_b128 v[192:195], v169 offset:2064
	v_mfma_f32_16x16x32_f16 v[80:83], v[160:163], v[238:241], v[80:83]
	ds_read_b128 v[144:147], v168 offset:3088
	ds_read_b128 v[196:199], v169 offset:3088
	v_mfma_f32_16x16x32_f16 v[84:87], v[148:151], v[242:245], v[84:87]
	v_mfma_f32_16x16x32_f16 v[88:91], v[152:155], v[242:245], v[88:91]
	v_mfma_f32_16x16x32_f16 v[92:95], v[156:159], v[242:245], v[92:95]
	v_mfma_f32_16x16x32_f16 v[96:99], v[160:163], v[242:245], v[96:99]
	v_mfma_f32_16x16x32_f16 v[100:103], v[148:151], v[246:249], v[100:103]
	v_mfma_f32_16x16x32_f16 v[104:107], v[152:155], v[246:249], v[104:107]
	v_mfma_f32_16x16x32_f16 v[108:111], v[156:159], v[246:249], v[108:111]
	v_mfma_f32_16x16x32_f16 v[112:115], v[160:163], v[246:249], v[112:115]
	v_mfma_f32_16x16x32_f16 v[116:119], v[148:151], v[250:253], v[116:119]
	v_mfma_f32_16x16x32_f16 v[120:123], v[152:155], v[250:253], v[120:123]
	v_mfma_f32_16x16x32_f16 v[124:127], v[156:159], v[250:253], v[124:127]
	v_mfma_f32_16x16x32_f16 v[128:131], v[160:163], v[250:253], v[128:131]
	s_waitcnt lgkmcnt(0)
	s_mov_b32 s32, s37
	v_add_u32_e32 v169, s32, v164
	v_mfma_f32_16x16x32_f16 v[4:7], v[132:135], v[184:187], v[4:7]
	ds_read_b128 v[238:241], v169 offset:4112
	v_mfma_f32_16x16x32_f16 v[8:11], v[136:139], v[184:187], v[8:11]
	ds_read_b128 v[242:245], v169 offset:5136
	v_mfma_f32_16x16x32_f16 v[12:15], v[140:143], v[184:187], v[12:15]
	ds_read_b128 v[246:249], v169 offset:6160
	v_mfma_f32_16x16x32_f16 v[16:19], v[144:147], v[184:187], v[16:19]
	ds_read_b128 v[250:253], v169 offset:7184
	v_mfma_f32_16x16x32_f16 v[20:23], v[132:135], v[188:191], v[20:23]
	v_mfma_f32_16x16x32_f16 v[24:27], v[136:139], v[188:191], v[24:27]
	v_mfma_f32_16x16x32_f16 v[28:31], v[140:143], v[188:191], v[28:31]
	v_mfma_f32_16x16x32_f16 v[32:35], v[144:147], v[188:191], v[32:35]
	v_mfma_f32_16x16x32_f16 v[36:39], v[132:135], v[192:195], v[36:39]
	v_mfma_f32_16x16x32_f16 v[40:43], v[136:139], v[192:195], v[40:43]
	v_mfma_f32_16x16x32_f16 v[44:47], v[140:143], v[192:195], v[44:47]
	v_mfma_f32_16x16x32_f16 v[48:51], v[144:147], v[192:195], v[48:51]
	v_mfma_f32_16x16x32_f16 v[52:55], v[132:135], v[196:199], v[52:55]
	v_mfma_f32_16x16x32_f16 v[56:59], v[136:139], v[196:199], v[56:59]
	v_mfma_f32_16x16x32_f16 v[60:63], v[140:143], v[196:199], v[60:63]
	v_mfma_f32_16x16x32_f16 v[64:67], v[144:147], v[196:199], v[64:67]
	s_waitcnt vmcnt(0) lgkmcnt(0)
	s_barrier
	s_add_i32 s37, s32, 0x8000
	s_cmp_lg_u32 s32, 0x18000
	s_cselect_b32 s37, s37, 0
	v_add_u32_e32 v168, s37, v165
	v_add_u32_e32 v169, s37, v164
	v_mfma_f32_16x16x32_f16 v[68:71], v[132:135], v[238:241], v[68:71]
	ds_read_b128 v[148:151], v168 offset:16
	ds_read_b128 v[184:187], v169 offset:16
	v_mfma_f32_16x16x32_f16 v[72:75], v[136:139], v[238:241], v[72:75]
	ds_read_b128 v[152:155], v168 offset:1040
	ds_read_b128 v[188:191], v169 offset:1040
	v_mfma_f32_16x16x32_f16 v[76:79], v[140:143], v[238:241], v[76:79]
	ds_read_b128 v[156:159], v168 offset:2064
	ds_read_b128 v[192:195], v169 offset:2064
	v_mfma_f32_16x16x32_f16 v[80:83], v[144:147], v[238:241], v[80:83]
	ds_read_b128 v[160:163], v168 offset:3088
	ds_read_b128 v[196:199], v169 offset:3088
	v_mfma_f32_16x16x32_f16 v[84:87], v[132:135], v[242:245], v[84:87]
	v_mfma_f32_16x16x32_f16 v[88:91], v[136:139], v[242:245], v[88:91]
	v_mfma_f32_16x16x32_f16 v[92:95], v[140:143], v[242:245], v[92:95]
	v_mfma_f32_16x16x32_f16 v[96:99], v[144:147], v[242:245], v[96:99]
	v_mfma_f32_16x16x32_f16 v[100:103], v[132:135], v[246:249], v[100:103]
	v_mfma_f32_16x16x32_f16 v[104:107], v[136:139], v[246:249], v[104:107]
	v_mfma_f32_16x16x32_f16 v[108:111], v[140:143], v[246:249], v[108:111]
	v_mfma_f32_16x16x32_f16 v[112:115], v[144:147], v[246:249], v[112:115]
	v_mfma_f32_16x16x32_f16 v[116:119], v[132:135], v[250:253], v[116:119]
	v_mfma_f32_16x16x32_f16 v[120:123], v[136:139], v[250:253], v[120:123]
	v_mfma_f32_16x16x32_f16 v[124:127], v[140:143], v[250:253], v[124:127]
	v_mfma_f32_16x16x32_f16 v[128:131], v[144:147], v[250:253], v[128:131]
	s_waitcnt lgkmcnt(0)
	s_mov_b32 s32, s37
	v_add_u32_e32 v169, s32, v164
	v_mfma_f32_16x16x32_f16 v[4:7], v[148:151], v[184:187], v[4:7]
	ds_read_b128 v[238:241], v169 offset:4112
	v_mfma_f32_16x16x32_f16 v[8:11], v[152:155], v[184:187], v[8:11]
	ds_read_b128 v[242:245], v169 offset:5136
	v_mfma_f32_16x16x32_f16 v[12:15], v[156:159], v[184:187], v[12:15]
	ds_read_b128 v[246:249], v169 offset:6160
	v_mfma_f32_16x16x32_f16 v[16:19], v[160:163], v[184:187], v[16:19]
	ds_read_b128 v[250:253], v169 offset:7184
	v_mfma_f32_16x16x32_f16 v[20:23], v[148:151], v[188:191], v[20:23]
	v_mfma_f32_16x16x32_f16 v[24:27], v[152:155], v[188:191], v[24:27]
	v_mfma_f32_16x16x32_f16 v[28:31], v[156:159], v[188:191], v[28:31]
	v_mfma_f32_16x16x32_f16 v[32:35], v[160:163], v[188:191], v[32:35]
	v_mfma_f32_16x16x32_f16 v[36:39], v[148:151], v[192:195], v[36:39]
	v_mfma_f32_16x16x32_f16 v[40:43], v[152:155], v[192:195], v[40:43]
	v_mfma_f32_16x16x32_f16 v[44:47], v[156:159], v[192:195], v[44:47]
	v_mfma_f32_16x16x32_f16 v[48:51], v[160:163], v[192:195], v[48:51]
	v_mfma_f32_16x16x32_f16 v[52:55], v[148:151], v[196:199], v[52:55]
	v_mfma_f32_16x16x32_f16 v[56:59], v[152:155], v[196:199], v[56:59]
	v_mfma_f32_16x16x32_f16 v[60:63], v[156:159], v[196:199], v[60:63]
	v_mfma_f32_16x16x32_f16 v[64:67], v[160:163], v[196:199], v[64:67]
	s_waitcnt lgkmcnt(0)
	s_barrier
	v_mfma_f32_16x16x32_f16 v[68:71], v[148:151], v[238:241], v[68:71]
	v_mfma_f32_16x16x32_f16 v[72:75], v[152:155], v[238:241], v[72:75]
	v_mfma_f32_16x16x32_f16 v[76:79], v[156:159], v[238:241], v[76:79]
	v_mfma_f32_16x16x32_f16 v[80:83], v[160:163], v[238:241], v[80:83]
	v_mfma_f32_16x16x32_f16 v[84:87], v[148:151], v[242:245], v[84:87]
	v_mfma_f32_16x16x32_f16 v[88:91], v[152:155], v[242:245], v[88:91]
	v_mfma_f32_16x16x32_f16 v[92:95], v[156:159], v[242:245], v[92:95]
	v_mfma_f32_16x16x32_f16 v[96:99], v[160:163], v[242:245], v[96:99]
	v_mfma_f32_16x16x32_f16 v[100:103], v[148:151], v[246:249], v[100:103]
	v_mfma_f32_16x16x32_f16 v[104:107], v[152:155], v[246:249], v[104:107]
	v_mfma_f32_16x16x32_f16 v[108:111], v[156:159], v[246:249], v[108:111]
	v_mfma_f32_16x16x32_f16 v[112:115], v[160:163], v[246:249], v[112:115]
	v_mfma_f32_16x16x32_f16 v[116:119], v[148:151], v[250:253], v[116:119]
	v_mfma_f32_16x16x32_f16 v[120:123], v[152:155], v[250:253], v[120:123]
	v_mfma_f32_16x16x32_f16 v[124:127], v[156:159], v[250:253], v[124:127]
	v_mfma_f32_16x16x32_f16 v[128:131], v[160:163], v[250:253], v[128:131]
	s_lshl_b64 s[80:81], s[28:29], 13
	s_add_u32 s80, s80, s34
	s_addc_u32 s81, s81, s35
	s_lshl_b32 s82, s65, 1
	s_add_u32 s80, s80, s82
	s_addc_u32 s81, s81, 0
	v_and_b32_e32 v172, 15, v200
	v_bfe_u32 v173, v200, 4, 2
	v_bfe_u32 v174, v200, 6, 2
	v_bfe_u32 v175, v200, 8, 1
	v_lshl_or_b32 v175, v175, 7, v172
	v_lshlrev_b32_e32 v175, 13, v175
	v_lshlrev_b32_e32 v174, 6, v174
	v_lshl_or_b32 v174, v173, 2, v174
	v_lshl_add_u32 v177, v174, 1, v175
	v_and_b32_e32 v172, 1, v173
	v_mul_u32_u24_e32 v172, 24, v172
	v_add_u32_e32 v177, v177, v172
	v_max_f32_e32 v4, 0, v4
	v_max_f32_e32 v5, 0, v5
	v_max_f32_e32 v6, 0, v6
	v_max_f32_e32 v7, 0, v7
	v_pk_mul_f32 v[4:5], v[4:5], v[4:5]
	v_pk_mul_f32 v[6:7], v[6:7], v[6:7]
	v_cvt_pk_f16_f32 v172, v4, v5
	v_cvt_pk_f16_f32 v173, v6, v7
	v_max_f32_e32 v8, 0, v8
	v_max_f32_e32 v9, 0, v9
	v_max_f32_e32 v10, 0, v10
	v_max_f32_e32 v11, 0, v11
	v_pk_mul_f32 v[8:9], v[8:9], v[8:9]
	v_pk_mul_f32 v[10:11], v[10:11], v[10:11]
	v_cvt_pk_f16_f32 v174, v8, v9
	v_cvt_pk_f16_f32 v175, v10, v11
	s_nop 1
	v_permlane16_swap_b32_e32 v172, v174
	v_permlane16_swap_b32_e32 v173, v175
	global_store_dwordx4 v177, v[172:175], s[80:81] nt
	v_max_f32_e32 v12, 0, v12
	v_max_f32_e32 v13, 0, v13
	v_max_f32_e32 v14, 0, v14
	v_max_f32_e32 v15, 0, v15
	v_pk_mul_f32 v[12:13], v[12:13], v[12:13]
	v_pk_mul_f32 v[14:15], v[14:15], v[14:15]
	v_cvt_pk_f16_f32 v228, v12, v13
	v_cvt_pk_f16_f32 v229, v14, v15
	v_max_f32_e32 v16, 0, v16
	v_max_f32_e32 v17, 0, v17
	v_max_f32_e32 v18, 0, v18
	v_max_f32_e32 v19, 0, v19
	v_pk_mul_f32 v[16:17], v[16:17], v[16:17]
	v_pk_mul_f32 v[18:19], v[18:19], v[18:19]
	v_cvt_pk_f16_f32 v230, v16, v17
	v_cvt_pk_f16_f32 v231, v18, v19
	s_nop 1
	v_permlane16_swap_b32_e32 v228, v230
	v_permlane16_swap_b32_e32 v229, v231
	global_store_dwordx4 v177, v[228:231], s[80:81] offset:64 nt
	v_add_u32_e32 v177, 0x20000, v177
	v_max_f32_e32 v20, 0, v20
	v_max_f32_e32 v21, 0, v21
	v_max_f32_e32 v22, 0, v22
	v_max_f32_e32 v23, 0, v23
	v_pk_mul_f32 v[20:21], v[20:21], v[20:21]
	v_pk_mul_f32 v[22:23], v[22:23], v[22:23]
	v_cvt_pk_f16_f32 v172, v20, v21
	v_cvt_pk_f16_f32 v173, v22, v23
	v_max_f32_e32 v24, 0, v24
	v_max_f32_e32 v25, 0, v25
	v_max_f32_e32 v26, 0, v26
	v_max_f32_e32 v27, 0, v27
	v_pk_mul_f32 v[24:25], v[24:25], v[24:25]
	v_pk_mul_f32 v[26:27], v[26:27], v[26:27]
	v_cvt_pk_f16_f32 v174, v24, v25
	v_cvt_pk_f16_f32 v175, v26, v27
	s_nop 1
	v_permlane16_swap_b32_e32 v172, v174
	v_permlane16_swap_b32_e32 v173, v175
	global_store_dwordx4 v177, v[172:175], s[80:81] nt
	v_max_f32_e32 v28, 0, v28
	v_max_f32_e32 v29, 0, v29
	v_max_f32_e32 v30, 0, v30
	v_max_f32_e32 v31, 0, v31
	v_pk_mul_f32 v[28:29], v[28:29], v[28:29]
	v_pk_mul_f32 v[30:31], v[30:31], v[30:31]
	v_cvt_pk_f16_f32 v228, v28, v29
	v_cvt_pk_f16_f32 v229, v30, v31
	v_max_f32_e32 v32, 0, v32
	v_max_f32_e32 v33, 0, v33
	v_max_f32_e32 v34, 0, v34
	v_max_f32_e32 v35, 0, v35
	v_pk_mul_f32 v[32:33], v[32:33], v[32:33]
	v_pk_mul_f32 v[34:35], v[34:35], v[34:35]
	v_cvt_pk_f16_f32 v230, v32, v33
	v_cvt_pk_f16_f32 v231, v34, v35
	s_nop 1
	v_permlane16_swap_b32_e32 v228, v230
	v_permlane16_swap_b32_e32 v229, v231
	global_store_dwordx4 v177, v[228:231], s[80:81] offset:64 nt
	v_add_u32_e32 v177, 0x20000, v177
	v_max_f32_e32 v36, 0, v36
	v_max_f32_e32 v37, 0, v37
	v_max_f32_e32 v38, 0, v38
	v_max_f32_e32 v39, 0, v39
	v_pk_mul_f32 v[36:37], v[36:37], v[36:37]
	v_pk_mul_f32 v[38:39], v[38:39], v[38:39]
	v_cvt_pk_f16_f32 v172, v36, v37
	v_cvt_pk_f16_f32 v173, v38, v39
	v_max_f32_e32 v40, 0, v40
	v_max_f32_e32 v41, 0, v41
	v_max_f32_e32 v42, 0, v42
	v_max_f32_e32 v43, 0, v43
	v_pk_mul_f32 v[40:41], v[40:41], v[40:41]
	v_pk_mul_f32 v[42:43], v[42:43], v[42:43]
	v_cvt_pk_f16_f32 v174, v40, v41
	v_cvt_pk_f16_f32 v175, v42, v43
	s_nop 1
	v_permlane16_swap_b32_e32 v172, v174
	v_permlane16_swap_b32_e32 v173, v175
	global_store_dwordx4 v177, v[172:175], s[80:81] nt
	v_max_f32_e32 v44, 0, v44
	v_max_f32_e32 v45, 0, v45
	v_max_f32_e32 v46, 0, v46
	v_max_f32_e32 v47, 0, v47
	v_pk_mul_f32 v[44:45], v[44:45], v[44:45]
	v_pk_mul_f32 v[46:47], v[46:47], v[46:47]
	v_cvt_pk_f16_f32 v228, v44, v45
	v_cvt_pk_f16_f32 v229, v46, v47
	v_max_f32_e32 v48, 0, v48
	v_max_f32_e32 v49, 0, v49
	v_max_f32_e32 v50, 0, v50
	v_max_f32_e32 v51, 0, v51
	v_pk_mul_f32 v[48:49], v[48:49], v[48:49]
	v_pk_mul_f32 v[50:51], v[50:51], v[50:51]
	v_cvt_pk_f16_f32 v230, v48, v49
	v_cvt_pk_f16_f32 v231, v50, v51
	s_nop 1
	v_permlane16_swap_b32_e32 v228, v230
	v_permlane16_swap_b32_e32 v229, v231
	global_store_dwordx4 v177, v[228:231], s[80:81] offset:64 nt
	v_add_u32_e32 v177, 0x20000, v177
	v_max_f32_e32 v52, 0, v52
	v_max_f32_e32 v53, 0, v53
	v_max_f32_e32 v54, 0, v54
	v_max_f32_e32 v55, 0, v55
	v_pk_mul_f32 v[52:53], v[52:53], v[52:53]
	v_pk_mul_f32 v[54:55], v[54:55], v[54:55]
	v_cvt_pk_f16_f32 v172, v52, v53
	v_cvt_pk_f16_f32 v173, v54, v55
	v_max_f32_e32 v56, 0, v56
	v_max_f32_e32 v57, 0, v57
	v_max_f32_e32 v58, 0, v58
	v_max_f32_e32 v59, 0, v59
	v_pk_mul_f32 v[56:57], v[56:57], v[56:57]
	v_pk_mul_f32 v[58:59], v[58:59], v[58:59]
	v_cvt_pk_f16_f32 v174, v56, v57
	v_cvt_pk_f16_f32 v175, v58, v59
	s_nop 1
	v_permlane16_swap_b32_e32 v172, v174
	v_permlane16_swap_b32_e32 v173, v175
	global_store_dwordx4 v177, v[172:175], s[80:81] nt
	v_max_f32_e32 v60, 0, v60
	v_max_f32_e32 v61, 0, v61
	v_max_f32_e32 v62, 0, v62
	v_max_f32_e32 v63, 0, v63
	v_pk_mul_f32 v[60:61], v[60:61], v[60:61]
	v_pk_mul_f32 v[62:63], v[62:63], v[62:63]
	v_cvt_pk_f16_f32 v228, v60, v61
	v_cvt_pk_f16_f32 v229, v62, v63
	v_max_f32_e32 v64, 0, v64
	v_max_f32_e32 v65, 0, v65
	v_max_f32_e32 v66, 0, v66
	v_max_f32_e32 v67, 0, v67
	v_pk_mul_f32 v[64:65], v[64:65], v[64:65]
	v_pk_mul_f32 v[66:67], v[66:67], v[66:67]
	v_cvt_pk_f16_f32 v230, v64, v65
	v_cvt_pk_f16_f32 v231, v66, v67
	s_nop 1
	v_permlane16_swap_b32_e32 v228, v230
	v_permlane16_swap_b32_e32 v229, v231
	global_store_dwordx4 v177, v[228:231], s[80:81] offset:64 nt
	v_add_u32_e32 v177, 0x20000, v177
	v_max_f32_e32 v68, 0, v68
	v_max_f32_e32 v69, 0, v69
	v_max_f32_e32 v70, 0, v70
	v_max_f32_e32 v71, 0, v71
	v_pk_mul_f32 v[68:69], v[68:69], v[68:69]
	v_pk_mul_f32 v[70:71], v[70:71], v[70:71]
	v_cvt_pk_f16_f32 v172, v68, v69
	v_cvt_pk_f16_f32 v173, v70, v71
	v_max_f32_e32 v72, 0, v72
	v_max_f32_e32 v73, 0, v73
	v_max_f32_e32 v74, 0, v74
	v_max_f32_e32 v75, 0, v75
	v_pk_mul_f32 v[72:73], v[72:73], v[72:73]
	v_pk_mul_f32 v[74:75], v[74:75], v[74:75]
	v_cvt_pk_f16_f32 v174, v72, v73
	v_cvt_pk_f16_f32 v175, v74, v75
	s_nop 1
	v_permlane16_swap_b32_e32 v172, v174
	v_permlane16_swap_b32_e32 v173, v175
	global_store_dwordx4 v177, v[172:175], s[80:81] nt
	v_max_f32_e32 v76, 0, v76
	v_max_f32_e32 v77, 0, v77
	v_max_f32_e32 v78, 0, v78
	v_max_f32_e32 v79, 0, v79
	v_pk_mul_f32 v[76:77], v[76:77], v[76:77]
	v_pk_mul_f32 v[78:79], v[78:79], v[78:79]
	v_cvt_pk_f16_f32 v228, v76, v77
	v_cvt_pk_f16_f32 v229, v78, v79
	v_max_f32_e32 v80, 0, v80
	v_max_f32_e32 v81, 0, v81
	v_max_f32_e32 v82, 0, v82
	v_max_f32_e32 v83, 0, v83
	v_pk_mul_f32 v[80:81], v[80:81], v[80:81]
	v_pk_mul_f32 v[82:83], v[82:83], v[82:83]
	v_cvt_pk_f16_f32 v230, v80, v81
	v_cvt_pk_f16_f32 v231, v82, v83
	s_nop 1
	v_permlane16_swap_b32_e32 v228, v230
	v_permlane16_swap_b32_e32 v229, v231
	global_store_dwordx4 v177, v[228:231], s[80:81] offset:64 nt
	v_add_u32_e32 v177, 0x20000, v177
	v_max_f32_e32 v84, 0, v84
	v_max_f32_e32 v85, 0, v85
	v_max_f32_e32 v86, 0, v86
	v_max_f32_e32 v87, 0, v87
	v_pk_mul_f32 v[84:85], v[84:85], v[84:85]
	v_pk_mul_f32 v[86:87], v[86:87], v[86:87]
	v_cvt_pk_f16_f32 v172, v84, v85
	v_cvt_pk_f16_f32 v173, v86, v87
	v_max_f32_e32 v88, 0, v88
	v_max_f32_e32 v89, 0, v89
	v_max_f32_e32 v90, 0, v90
	v_max_f32_e32 v91, 0, v91
	v_pk_mul_f32 v[88:89], v[88:89], v[88:89]
	v_pk_mul_f32 v[90:91], v[90:91], v[90:91]
	v_cvt_pk_f16_f32 v174, v88, v89
	v_cvt_pk_f16_f32 v175, v90, v91
	s_nop 1
	v_permlane16_swap_b32_e32 v172, v174
	v_permlane16_swap_b32_e32 v173, v175
	global_store_dwordx4 v177, v[172:175], s[80:81] nt
	v_max_f32_e32 v92, 0, v92
	v_max_f32_e32 v93, 0, v93
	v_max_f32_e32 v94, 0, v94
	v_max_f32_e32 v95, 0, v95
	v_pk_mul_f32 v[92:93], v[92:93], v[92:93]
	v_pk_mul_f32 v[94:95], v[94:95], v[94:95]
	v_cvt_pk_f16_f32 v228, v92, v93
	v_cvt_pk_f16_f32 v229, v94, v95
	v_max_f32_e32 v96, 0, v96
	v_max_f32_e32 v97, 0, v97
	v_max_f32_e32 v98, 0, v98
	v_max_f32_e32 v99, 0, v99
	v_pk_mul_f32 v[96:97], v[96:97], v[96:97]
	v_pk_mul_f32 v[98:99], v[98:99], v[98:99]
	v_cvt_pk_f16_f32 v230, v96, v97
	v_cvt_pk_f16_f32 v231, v98, v99
	s_nop 1
	v_permlane16_swap_b32_e32 v228, v230
	v_permlane16_swap_b32_e32 v229, v231
	global_store_dwordx4 v177, v[228:231], s[80:81] offset:64 nt
	v_add_u32_e32 v177, 0x20000, v177
	v_max_f32_e32 v100, 0, v100
	v_max_f32_e32 v101, 0, v101
	v_max_f32_e32 v102, 0, v102
	v_max_f32_e32 v103, 0, v103
	v_pk_mul_f32 v[100:101], v[100:101], v[100:101]
	v_pk_mul_f32 v[102:103], v[102:103], v[102:103]
	v_cvt_pk_f16_f32 v172, v100, v101
	v_cvt_pk_f16_f32 v173, v102, v103
	v_max_f32_e32 v104, 0, v104
	v_max_f32_e32 v105, 0, v105
	v_max_f32_e32 v106, 0, v106
	v_max_f32_e32 v107, 0, v107
	v_pk_mul_f32 v[104:105], v[104:105], v[104:105]
	v_pk_mul_f32 v[106:107], v[106:107], v[106:107]
	v_cvt_pk_f16_f32 v174, v104, v105
	v_cvt_pk_f16_f32 v175, v106, v107
	s_nop 1
	v_permlane16_swap_b32_e32 v172, v174
	v_permlane16_swap_b32_e32 v173, v175
	global_store_dwordx4 v177, v[172:175], s[80:81] nt
	v_max_f32_e32 v108, 0, v108
	v_max_f32_e32 v109, 0, v109
	v_max_f32_e32 v110, 0, v110
	v_max_f32_e32 v111, 0, v111
	v_pk_mul_f32 v[108:109], v[108:109], v[108:109]
	v_pk_mul_f32 v[110:111], v[110:111], v[110:111]
	v_cvt_pk_f16_f32 v228, v108, v109
	v_cvt_pk_f16_f32 v229, v110, v111
	v_max_f32_e32 v112, 0, v112
	v_max_f32_e32 v113, 0, v113
	v_max_f32_e32 v114, 0, v114
	v_max_f32_e32 v115, 0, v115
	v_pk_mul_f32 v[112:113], v[112:113], v[112:113]
	v_pk_mul_f32 v[114:115], v[114:115], v[114:115]
	v_cvt_pk_f16_f32 v230, v112, v113
	v_cvt_pk_f16_f32 v231, v114, v115
	s_nop 1
	v_permlane16_swap_b32_e32 v228, v230
	v_permlane16_swap_b32_e32 v229, v231
	global_store_dwordx4 v177, v[228:231], s[80:81] offset:64 nt
	v_add_u32_e32 v177, 0x20000, v177
	v_max_f32_e32 v116, 0, v116
	v_max_f32_e32 v117, 0, v117
	v_max_f32_e32 v118, 0, v118
	v_max_f32_e32 v119, 0, v119
	v_pk_mul_f32 v[116:117], v[116:117], v[116:117]
	v_pk_mul_f32 v[118:119], v[118:119], v[118:119]
	v_cvt_pk_f16_f32 v172, v116, v117
	v_cvt_pk_f16_f32 v173, v118, v119
	v_max_f32_e32 v120, 0, v120
	v_max_f32_e32 v121, 0, v121
	v_max_f32_e32 v122, 0, v122
	v_max_f32_e32 v123, 0, v123
	v_pk_mul_f32 v[120:121], v[120:121], v[120:121]
	v_pk_mul_f32 v[122:123], v[122:123], v[122:123]
	v_cvt_pk_f16_f32 v174, v120, v121
	v_cvt_pk_f16_f32 v175, v122, v123
	s_nop 1
	v_permlane16_swap_b32_e32 v172, v174
	v_permlane16_swap_b32_e32 v173, v175
	global_store_dwordx4 v177, v[172:175], s[80:81] nt
	v_max_f32_e32 v124, 0, v124
	v_max_f32_e32 v125, 0, v125
	v_max_f32_e32 v126, 0, v126
	v_max_f32_e32 v127, 0, v127
	v_pk_mul_f32 v[124:125], v[124:125], v[124:125]
	v_pk_mul_f32 v[126:127], v[126:127], v[126:127]
	v_cvt_pk_f16_f32 v228, v124, v125
	v_cvt_pk_f16_f32 v229, v126, v127
	v_max_f32_e32 v128, 0, v128
	v_max_f32_e32 v129, 0, v129
	v_max_f32_e32 v130, 0, v130
	v_max_f32_e32 v131, 0, v131
	v_pk_mul_f32 v[128:129], v[128:129], v[128:129]
	v_pk_mul_f32 v[130:131], v[130:131], v[130:131]
	v_cvt_pk_f16_f32 v230, v128, v129
	v_cvt_pk_f16_f32 v231, v130, v131
	s_nop 1
	v_permlane16_swap_b32_e32 v228, v230
	v_permlane16_swap_b32_e32 v229, v231
	global_store_dwordx4 v177, v[228:231], s[80:81] offset:64 nt
	s_nop 1
	s_add_i32 s56, s56, s76
	s_cmp_ge_i32 s56, s58
	s_cbranch_scc1 .LBB0_127
	s_branch .LBB0_111

.Lt_mlp1a:
	v_add_u32_e32 v169, s37, v164
	v_mfma_f32_16x16x32_f16 v[4:7], v[132:135], v[184:187], v[4:7]
	ds_read_b128 v[238:241], v169 offset:4112
	v_mfma_f32_16x16x32_f16 v[8:11], v[136:139], v[184:187], v[8:11]
	ds_read_b128 v[242:245], v169 offset:5136
	v_mfma_f32_16x16x32_f16 v[12:15], v[140:143], v[184:187], v[12:15]
	ds_read_b128 v[246:249], v169 offset:6160
	v_mfma_f32_16x16x32_f16 v[16:19], v[144:147], v[184:187], v[16:19]
	ds_read_b128 v[250:253], v169 offset:7184
	v_mfma_f32_16x16x32_f16 v[20:23], v[132:135], v[188:191], v[20:23]
	v_mfma_f32_16x16x32_f16 v[24:27], v[136:139], v[188:191], v[24:27]
	v_mfma_f32_16x16x32_f16 v[28:31], v[140:143], v[188:191], v[28:31]
	v_mfma_f32_16x16x32_f16 v[32:35], v[144:147], v[188:191], v[32:35]
	v_mfma_f32_16x16x32_f16 v[36:39], v[132:135], v[192:195], v[36:39]
	v_mfma_f32_16x16x32_f16 v[40:43], v[136:139], v[192:195], v[40:43]
	v_mfma_f32_16x16x32_f16 v[44:47], v[140:143], v[192:195], v[44:47]
	v_mfma_f32_16x16x32_f16 v[48:51], v[144:147], v[192:195], v[48:51]
	v_mfma_f32_16x16x32_f16 v[52:55], v[132:135], v[196:199], v[52:55]
	v_mfma_f32_16x16x32_f16 v[56:59], v[136:139], v[196:199], v[56:59]
	v_mfma_f32_16x16x32_f16 v[60:63], v[140:143], v[196:199], v[60:63]
	v_mfma_f32_16x16x32_f16 v[64:67], v[144:147], v[196:199], v[64:67]
	s_waitcnt vmcnt(8) lgkmcnt(0)
	s_barrier
	s_add_i32 s53, s37, 0x8000
	s_cmp_lg_u32 s37, 0x18000
	s_cselect_b32 s53, s53, 0
	v_add_u32_e32 v168, s53, v165
	v_add_u32_e32 v169, s53, v164
	s_add_u32 vcc_lo, s32, s37
	v_mfma_f32_16x16x32_f16 v[68:71], v[132:135], v[238:241], v[68:71]
	ds_read_b128 v[148:151], v168 offset:16
	ds_read_b128 v[184:187], v169 offset:16
	v_mfma_f32_16x16x32_f16 v[72:75], v[136:139], v[238:241], v[72:75]
	ds_read_b128 v[152:155], v168 offset:1040
	ds_read_b128 v[188:191], v169 offset:1040
	v_mfma_f32_16x16x32_f16 v[76:79], v[140:143], v[238:241], v[76:79]
	ds_read_b128 v[156:159], v168 offset:2064
	ds_read_b128 v[192:195], v169 offset:2064
	v_mfma_f32_16x16x32_f16 v[80:83], v[144:147], v[238:241], v[80:83]
	ds_read_b128 v[160:163], v168 offset:3088
	ds_read_b128 v[196:199], v169 offset:3088
	v_mfma_f32_16x16x32_f16 v[84:87], v[132:135], v[242:245], v[84:87]
	v_mfma_f32_16x16x32_f16 v[88:91], v[136:139], v[242:245], v[88:91]
	v_mfma_f32_16x16x32_f16 v[92:95], v[140:143], v[242:245], v[92:95]
	v_mfma_f32_16x16x32_f16 v[96:99], v[144:147], v[242:245], v[96:99]
	v_mfma_f32_16x16x32_f16 v[100:103], v[132:135], v[246:249], v[100:103]
	s_mov_b32 m0, vcc_lo
	s_nop 0
	global_load_lds_dwordx4 v170, s[30:31]
	v_mfma_f32_16x16x32_f16 v[104:107], v[136:139], v[246:249], v[104:107]
	s_add_u32 m0, vcc_lo, 0x400
	s_nop 0
	global_load_lds_dwordx4 v171, s[30:31]
	v_mfma_f32_16x16x32_f16 v[108:111], v[140:143], v[246:249], v[108:111]
	s_add_u32 m0, vcc_lo, 0x4000
	s_nop 0
	global_load_lds_dwordx4 v170, s[56:57]
	v_mfma_f32_16x16x32_f16 v[112:115], v[144:147], v[246:249], v[112:115]
	s_add_u32 m0, vcc_lo, 0x4400
	s_nop 0
	global_load_lds_dwordx4 v171, s[56:57]
	v_mfma_f32_16x16x32_f16 v[116:119], v[132:135], v[250:253], v[116:119]
	v_mfma_f32_16x16x32_f16 v[120:123], v[136:139], v[250:253], v[120:123]
	v_mfma_f32_16x16x32_f16 v[124:127], v[140:143], v[250:253], v[124:127]
	v_mfma_f32_16x16x32_f16 v[128:131], v[144:147], v[250:253], v[128:131]
	s_waitcnt lgkmcnt(0)
	s_mov_b32 s37, s53
	s_add_u32 s30, s30, 64
	s_addc_u32 s31, s31, 0
	s_add_u32 s56, s56, 64
	s_addc_u32 s57, s57, 0
	v_add_u32_e32 v169, s37, v164
	v_mfma_f32_16x16x32_f16 v[4:7], v[148:151], v[184:187], v[4:7]
	ds_read_b128 v[238:241], v169 offset:4112
	v_mfma_f32_16x16x32_f16 v[8:11], v[152:155], v[184:187], v[8:11]
	ds_read_b128 v[242:245], v169 offset:5136
	v_mfma_f32_16x16x32_f16 v[12:15], v[156:159], v[184:187], v[12:15]
	ds_read_b128 v[246:249], v169 offset:6160
	v_mfma_f32_16x16x32_f16 v[16:19], v[160:163], v[184:187], v[16:19]
	ds_read_b128 v[250:253], v169 offset:7184
	v_mfma_f32_16x16x32_f16 v[20:23], v[148:151], v[188:191], v[20:23]
	v_mfma_f32_16x16x32_f16 v[24:27], v[152:155], v[188:191], v[24:27]
	v_mfma_f32_16x16x32_f16 v[28:31], v[156:159], v[188:191], v[28:31]
	v_mfma_f32_16x16x32_f16 v[32:35], v[160:163], v[188:191], v[32:35]
	v_mfma_f32_16x16x32_f16 v[36:39], v[148:151], v[192:195], v[36:39]
	v_mfma_f32_16x16x32_f16 v[40:43], v[152:155], v[192:195], v[40:43]
	v_mfma_f32_16x16x32_f16 v[44:47], v[156:159], v[192:195], v[44:47]
	v_mfma_f32_16x16x32_f16 v[48:51], v[160:163], v[192:195], v[48:51]
	v_mfma_f32_16x16x32_f16 v[52:55], v[148:151], v[196:199], v[52:55]
	v_mfma_f32_16x16x32_f16 v[56:59], v[152:155], v[196:199], v[56:59]
	v_mfma_f32_16x16x32_f16 v[60:63], v[156:159], v[196:199], v[60:63]
	v_mfma_f32_16x16x32_f16 v[64:67], v[160:163], v[196:199], v[64:67]
	s_waitcnt vmcnt(8) lgkmcnt(0)
	s_barrier
	s_add_i32 s53, s37, 0x8000
	s_cmp_lg_u32 s37, 0x18000
	s_cselect_b32 s53, s53, 0
	v_add_u32_e32 v168, s53, v165
	v_add_u32_e32 v169, s53, v164
	s_add_u32 vcc_lo, s32, s37
	v_mfma_f32_16x16x32_f16 v[68:71], v[148:151], v[238:241], v[68:71]
	ds_read_b128 v[132:135], v168 offset:16
	ds_read_b128 v[184:187], v169 offset:16
	v_mfma_f32_16x16x32_f16 v[72:75], v[152:155], v[238:241], v[72:75]
	ds_read_b128 v[136:139], v168 offset:1040
	ds_read_b128 v[188:191], v169 offset:1040
	v_mfma_f32_16x16x32_f16 v[76:79], v[156:159], v[238:241], v[76:79]
	ds_read_b128 v[140:143], v168 offset:2064
	ds_read_b128 v[192:195], v169 offset:2064
	v_mfma_f32_16x16x32_f16 v[80:83], v[160:163], v[238:241], v[80:83]
	ds_read_b128 v[144:147], v168 offset:3088
	ds_read_b128 v[196:199], v169 offset:3088
	v_mfma_f32_16x16x32_f16 v[84:87], v[148:151], v[242:245], v[84:87]
	v_mfma_f32_16x16x32_f16 v[88:91], v[152:155], v[242:245], v[88:91]
	v_mfma_f32_16x16x32_f16 v[92:95], v[156:159], v[242:245], v[92:95]
	v_mfma_f32_16x16x32_f16 v[96:99], v[160:163], v[242:245], v[96:99]
	v_mfma_f32_16x16x32_f16 v[100:103], v[148:151], v[246:249], v[100:103]
	s_mov_b32 m0, vcc_lo
	s_nop 0
	global_load_lds_dwordx4 v170, s[30:31]
	v_mfma_f32_16x16x32_f16 v[104:107], v[152:155], v[246:249], v[104:107]
	s_add_u32 m0, vcc_lo, 0x400
	s_nop 0
	global_load_lds_dwordx4 v171, s[30:31]
	v_mfma_f32_16x16x32_f16 v[108:111], v[156:159], v[246:249], v[108:111]
	s_add_u32 m0, vcc_lo, 0x4000
	s_nop 0
	global_load_lds_dwordx4 v170, s[56:57]
	v_mfma_f32_16x16x32_f16 v[112:115], v[160:163], v[246:249], v[112:115]
	s_add_u32 m0, vcc_lo, 0x4400
	s_nop 0
	global_load_lds_dwordx4 v171, s[56:57]
	v_mfma_f32_16x16x32_f16 v[116:119], v[148:151], v[250:253], v[116:119]
	v_mfma_f32_16x16x32_f16 v[120:123], v[152:155], v[250:253], v[120:123]
	v_mfma_f32_16x16x32_f16 v[124:127], v[156:159], v[250:253], v[124:127]
	v_mfma_f32_16x16x32_f16 v[128:131], v[160:163], v[250:253], v[128:131]
	s_waitcnt lgkmcnt(0)
	s_mov_b32 s37, s53
	s_add_u32 s30, s30, 64
	s_addc_u32 s31, s31, 0
	s_add_u32 s56, s56, 64
	s_addc_u32 s57, s57, 0
	s_add_i32 s55, s55, 2
	s_cmp_lt_u32 s55, 28
	s_cbranch_scc1 .Lt_mlp1a
	v_add_u32_e32 v169, s37, v164
	v_mfma_f32_16x16x32_f16 v[4:7], v[132:135], v[184:187], v[4:7]
	ds_read_b128 v[238:241], v169 offset:4112
	v_mfma_f32_16x16x32_f16 v[8:11], v[136:139], v[184:187], v[8:11]
	ds_read_b128 v[242:245], v169 offset:5136
	v_mfma_f32_16x16x32_f16 v[12:15], v[140:143], v[184:187], v[12:15]
	ds_read_b128 v[246:249], v169 offset:6160
	v_mfma_f32_16x16x32_f16 v[16:19], v[144:147], v[184:187], v[16:19]
	ds_read_b128 v[250:253], v169 offset:7184
	v_mfma_f32_16x16x32_f16 v[20:23], v[132:135], v[188:191], v[20:23]
	v_mfma_f32_16x16x32_f16 v[24:27], v[136:139], v[188:191], v[24:27]
	v_mfma_f32_16x16x32_f16 v[28:31], v[140:143], v[188:191], v[28:31]
	v_mfma_f32_16x16x32_f16 v[32:35], v[144:147], v[188:191], v[32:35]
	v_mfma_f32_16x16x32_f16 v[36:39], v[132:135], v[192:195], v[36:39]
	v_mfma_f32_16x16x32_f16 v[40:43], v[136:139], v[192:195], v[40:43]
	v_mfma_f32_16x16x32_f16 v[44:47], v[140:143], v[192:195], v[44:47]
	v_mfma_f32_16x16x32_f16 v[48:51], v[144:147], v[192:195], v[48:51]
	v_mfma_f32_16x16x32_f16 v[52:55], v[132:135], v[196:199], v[52:55]
	v_mfma_f32_16x16x32_f16 v[56:59], v[136:139], v[196:199], v[56:59]
	v_mfma_f32_16x16x32_f16 v[60:63], v[140:143], v[196:199], v[60:63]
	v_mfma_f32_16x16x32_f16 v[64:67], v[144:147], v[196:199], v[64:67]
	s_waitcnt vmcnt(8) lgkmcnt(0)
	s_barrier
	s_add_i32 s53, s37, 0x8000
	s_cmp_lg_u32 s37, 0x18000
	s_cselect_b32 s53, s53, 0
	v_add_u32_e32 v168, s53, v165
	v_add_u32_e32 v169, s53, v164
	v_mfma_f32_16x16x32_f16 v[68:71], v[132:135], v[238:241], v[68:71]
	ds_read_b128 v[148:151], v168 offset:16
	ds_read_b128 v[184:187], v169 offset:16
	v_mfma_f32_16x16x32_f16 v[72:75], v[136:139], v[238:241], v[72:75]
	ds_read_b128 v[152:155], v168 offset:1040
	ds_read_b128 v[188:191], v169 offset:1040
	v_mfma_f32_16x16x32_f16 v[76:79], v[140:143], v[238:241], v[76:79]
	ds_read_b128 v[156:159], v168 offset:2064
	ds_read_b128 v[192:195], v169 offset:2064
	v_mfma_f32_16x16x32_f16 v[80:83], v[144:147], v[238:241], v[80:83]
	ds_read_b128 v[160:163], v168 offset:3088
	ds_read_b128 v[196:199], v169 offset:3088
	v_mfma_f32_16x16x32_f16 v[84:87], v[132:135], v[242:245], v[84:87]
	v_mfma_f32_16x16x32_f16 v[88:91], v[136:139], v[242:245], v[88:91]
	v_mfma_f32_16x16x32_f16 v[92:95], v[140:143], v[242:245], v[92:95]
	v_mfma_f32_16x16x32_f16 v[96:99], v[144:147], v[242:245], v[96:99]
	v_mfma_f32_16x16x32_f16 v[100:103], v[132:135], v[246:249], v[100:103]
	v_mfma_f32_16x16x32_f16 v[104:107], v[136:139], v[246:249], v[104:107]
	v_mfma_f32_16x16x32_f16 v[108:111], v[140:143], v[246:249], v[108:111]
	v_mfma_f32_16x16x32_f16 v[112:115], v[144:147], v[246:249], v[112:115]
	v_mfma_f32_16x16x32_f16 v[116:119], v[132:135], v[250:253], v[116:119]
	v_mfma_f32_16x16x32_f16 v[120:123], v[136:139], v[250:253], v[120:123]
	v_mfma_f32_16x16x32_f16 v[124:127], v[140:143], v[250:253], v[124:127]
	v_mfma_f32_16x16x32_f16 v[128:131], v[144:147], v[250:253], v[128:131]
	s_waitcnt lgkmcnt(0)
	s_mov_b32 s37, s53
	v_add_u32_e32 v169, s37, v164
	v_mfma_f32_16x16x32_f16 v[4:7], v[148:151], v[184:187], v[4:7]
	ds_read_b128 v[238:241], v169 offset:4112
	v_mfma_f32_16x16x32_f16 v[8:11], v[152:155], v[184:187], v[8:11]
	ds_read_b128 v[242:245], v169 offset:5136
	v_mfma_f32_16x16x32_f16 v[12:15], v[156:159], v[184:187], v[12:15]
	ds_read_b128 v[246:249], v169 offset:6160
	v_mfma_f32_16x16x32_f16 v[16:19], v[160:163], v[184:187], v[16:19]
	ds_read_b128 v[250:253], v169 offset:7184
	v_mfma_f32_16x16x32_f16 v[20:23], v[148:151], v[188:191], v[20:23]
	v_mfma_f32_16x16x32_f16 v[24:27], v[152:155], v[188:191], v[24:27]
	v_mfma_f32_16x16x32_f16 v[28:31], v[156:159], v[188:191], v[28:31]
	v_mfma_f32_16x16x32_f16 v[32:35], v[160:163], v[188:191], v[32:35]
	v_mfma_f32_16x16x32_f16 v[36:39], v[148:151], v[192:195], v[36:39]
	v_mfma_f32_16x16x32_f16 v[40:43], v[152:155], v[192:195], v[40:43]
	v_mfma_f32_16x16x32_f16 v[44:47], v[156:159], v[192:195], v[44:47]
	v_mfma_f32_16x16x32_f16 v[48:51], v[160:163], v[192:195], v[48:51]
	v_mfma_f32_16x16x32_f16 v[52:55], v[148:151], v[196:199], v[52:55]
	v_mfma_f32_16x16x32_f16 v[56:59], v[152:155], v[196:199], v[56:59]
	v_mfma_f32_16x16x32_f16 v[60:63], v[156:159], v[196:199], v[60:63]
	v_mfma_f32_16x16x32_f16 v[64:67], v[160:163], v[196:199], v[64:67]
	s_waitcnt vmcnt(4) lgkmcnt(0)
	s_barrier
	s_add_i32 s53, s37, 0x8000
	s_cmp_lg_u32 s37, 0x18000
	s_cselect_b32 s53, s53, 0
	v_add_u32_e32 v168, s53, v165
	v_add_u32_e32 v169, s53, v164
	v_mfma_f32_16x16x32_f16 v[68:71], v[148:151], v[238:241], v[68:71]
	ds_read_b128 v[132:135], v168 offset:16
	ds_read_b128 v[184:187], v169 offset:16
	v_mfma_f32_16x16x32_f16 v[72:75], v[152:155], v[238:241], v[72:75]
	ds_read_b128 v[136:139], v168 offset:1040
	ds_read_b128 v[188:191], v169 offset:1040
	v_mfma_f32_16x16x32_f16 v[76:79], v[156:159], v[238:241], v[76:79]
	ds_read_b128 v[140:143], v168 offset:2064
	ds_read_b128 v[192:195], v169 offset:2064
	v_mfma_f32_16x16x32_f16 v[80:83], v[160:163], v[238:241], v[80:83]
	ds_read_b128 v[144:147], v168 offset:3088
	ds_read_b128 v[196:199], v169 offset:3088
	v_mfma_f32_16x16x32_f16 v[84:87], v[148:151], v[242:245], v[84:87]
	v_mfma_f32_16x16x32_f16 v[88:91], v[152:155], v[242:245], v[88:91]
	v_mfma_f32_16x16x32_f16 v[92:95], v[156:159], v[242:245], v[92:95]
	v_mfma_f32_16x16x32_f16 v[96:99], v[160:163], v[242:245], v[96:99]
	v_mfma_f32_16x16x32_f16 v[100:103], v[148:151], v[246:249], v[100:103]
	v_mfma_f32_16x16x32_f16 v[104:107], v[152:155], v[246:249], v[104:107]
	v_mfma_f32_16x16x32_f16 v[108:111], v[156:159], v[246:249], v[108:111]
	v_mfma_f32_16x16x32_f16 v[112:115], v[160:163], v[246:249], v[112:115]
	v_mfma_f32_16x16x32_f16 v[116:119], v[148:151], v[250:253], v[116:119]
	v_mfma_f32_16x16x32_f16 v[120:123], v[152:155], v[250:253], v[120:123]
	v_mfma_f32_16x16x32_f16 v[124:127], v[156:159], v[250:253], v[124:127]
	v_mfma_f32_16x16x32_f16 v[128:131], v[160:163], v[250:253], v[128:131]
	s_waitcnt lgkmcnt(0)
	s_mov_b32 s37, s53
	v_add_u32_e32 v169, s37, v164
	v_mfma_f32_16x16x32_f16 v[4:7], v[132:135], v[184:187], v[4:7]
	ds_read_b128 v[238:241], v169 offset:4112
	v_mfma_f32_16x16x32_f16 v[8:11], v[136:139], v[184:187], v[8:11]
	ds_read_b128 v[242:245], v169 offset:5136
	v_mfma_f32_16x16x32_f16 v[12:15], v[140:143], v[184:187], v[12:15]
	ds_read_b128 v[246:249], v169 offset:6160
	v_mfma_f32_16x16x32_f16 v[16:19], v[144:147], v[184:187], v[16:19]
	ds_read_b128 v[250:253], v169 offset:7184
	v_mfma_f32_16x16x32_f16 v[20:23], v[132:135], v[188:191], v[20:23]
	v_mfma_f32_16x16x32_f16 v[24:27], v[136:139], v[188:191], v[24:27]
	v_mfma_f32_16x16x32_f16 v[28:31], v[140:143], v[188:191], v[28:31]
	v_mfma_f32_16x16x32_f16 v[32:35], v[144:147], v[188:191], v[32:35]
	v_mfma_f32_16x16x32_f16 v[36:39], v[132:135], v[192:195], v[36:39]
	v_mfma_f32_16x16x32_f16 v[40:43], v[136:139], v[192:195], v[40:43]
	v_mfma_f32_16x16x32_f16 v[44:47], v[140:143], v[192:195], v[44:47]
	v_mfma_f32_16x16x32_f16 v[48:51], v[144:147], v[192:195], v[48:51]
	v_mfma_f32_16x16x32_f16 v[52:55], v[132:135], v[196:199], v[52:55]
	v_mfma_f32_16x16x32_f16 v[56:59], v[136:139], v[196:199], v[56:59]
	v_mfma_f32_16x16x32_f16 v[60:63], v[140:143], v[196:199], v[60:63]
	v_mfma_f32_16x16x32_f16 v[64:67], v[144:147], v[196:199], v[64:67]
	s_waitcnt vmcnt(0) lgkmcnt(0)
	s_barrier
	s_add_i32 s53, s37, 0x8000
	s_cmp_lg_u32 s37, 0x18000
	s_cselect_b32 s53, s53, 0
	v_add_u32_e32 v168, s53, v165
	v_add_u32_e32 v169, s53, v164
	v_mfma_f32_16x16x32_f16 v[68:71], v[132:135], v[238:241], v[68:71]
	ds_read_b128 v[148:151], v168 offset:16
	ds_read_b128 v[184:187], v169 offset:16
	v_mfma_f32_16x16x32_f16 v[72:75], v[136:139], v[238:241], v[72:75]
	ds_read_b128 v[152:155], v168 offset:1040
	ds_read_b128 v[188:191], v169 offset:1040
	v_mfma_f32_16x16x32_f16 v[76:79], v[140:143], v[238:241], v[76:79]
	ds_read_b128 v[156:159], v168 offset:2064
	ds_read_b128 v[192:195], v169 offset:2064
	v_mfma_f32_16x16x32_f16 v[80:83], v[144:147], v[238:241], v[80:83]
	ds_read_b128 v[160:163], v168 offset:3088
	ds_read_b128 v[196:199], v169 offset:3088
	v_mfma_f32_16x16x32_f16 v[84:87], v[132:135], v[242:245], v[84:87]
	v_mfma_f32_16x16x32_f16 v[88:91], v[136:139], v[242:245], v[88:91]
	v_mfma_f32_16x16x32_f16 v[92:95], v[140:143], v[242:245], v[92:95]
	v_mfma_f32_16x16x32_f16 v[96:99], v[144:147], v[242:245], v[96:99]
	v_mfma_f32_16x16x32_f16 v[100:103], v[132:135], v[246:249], v[100:103]
	v_mfma_f32_16x16x32_f16 v[104:107], v[136:139], v[246:249], v[104:107]
	v_mfma_f32_16x16x32_f16 v[108:111], v[140:143], v[246:249], v[108:111]
	v_mfma_f32_16x16x32_f16 v[112:115], v[144:147], v[246:249], v[112:115]
	v_mfma_f32_16x16x32_f16 v[116:119], v[132:135], v[250:253], v[116:119]
	v_mfma_f32_16x16x32_f16 v[120:123], v[136:139], v[250:253], v[120:123]
	v_mfma_f32_16x16x32_f16 v[124:127], v[140:143], v[250:253], v[124:127]
	v_mfma_f32_16x16x32_f16 v[128:131], v[144:147], v[250:253], v[128:131]
	s_waitcnt lgkmcnt(0)
	s_mov_b32 s37, s53
	v_add_u32_e32 v169, s37, v164
	v_mfma_f32_16x16x32_f16 v[4:7], v[148:151], v[184:187], v[4:7]
	ds_read_b128 v[238:241], v169 offset:4112
	v_mfma_f32_16x16x32_f16 v[8:11], v[152:155], v[184:187], v[8:11]
	ds_read_b128 v[242:245], v169 offset:5136
	v_mfma_f32_16x16x32_f16 v[12:15], v[156:159], v[184:187], v[12:15]
	ds_read_b128 v[246:249], v169 offset:6160
	v_mfma_f32_16x16x32_f16 v[16:19], v[160:163], v[184:187], v[16:19]
	ds_read_b128 v[250:253], v169 offset:7184
	v_mfma_f32_16x16x32_f16 v[20:23], v[148:151], v[188:191], v[20:23]
	v_mfma_f32_16x16x32_f16 v[24:27], v[152:155], v[188:191], v[24:27]
	v_mfma_f32_16x16x32_f16 v[28:31], v[156:159], v[188:191], v[28:31]
	v_mfma_f32_16x16x32_f16 v[32:35], v[160:163], v[188:191], v[32:35]
	v_mfma_f32_16x16x32_f16 v[36:39], v[148:151], v[192:195], v[36:39]
	v_mfma_f32_16x16x32_f16 v[40:43], v[152:155], v[192:195], v[40:43]
	v_mfma_f32_16x16x32_f16 v[44:47], v[156:159], v[192:195], v[44:47]
	v_mfma_f32_16x16x32_f16 v[48:51], v[160:163], v[192:195], v[48:51]
	v_mfma_f32_16x16x32_f16 v[52:55], v[148:151], v[196:199], v[52:55]
	v_mfma_f32_16x16x32_f16 v[56:59], v[152:155], v[196:199], v[56:59]
	v_mfma_f32_16x16x32_f16 v[60:63], v[156:159], v[196:199], v[60:63]
	v_mfma_f32_16x16x32_f16 v[64:67], v[160:163], v[196:199], v[64:67]
	s_waitcnt lgkmcnt(0)
	s_barrier
	v_mfma_f32_16x16x32_f16 v[68:71], v[148:151], v[238:241], v[68:71]
	v_mfma_f32_16x16x32_f16 v[72:75], v[152:155], v[238:241], v[72:75]
	v_mfma_f32_16x16x32_f16 v[76:79], v[156:159], v[238:241], v[76:79]
	v_mfma_f32_16x16x32_f16 v[80:83], v[160:163], v[238:241], v[80:83]
	v_mfma_f32_16x16x32_f16 v[84:87], v[148:151], v[242:245], v[84:87]
	v_mfma_f32_16x16x32_f16 v[88:91], v[152:155], v[242:245], v[88:91]
	v_mfma_f32_16x16x32_f16 v[92:95], v[156:159], v[242:245], v[92:95]
	v_mfma_f32_16x16x32_f16 v[96:99], v[160:163], v[242:245], v[96:99]
	v_mfma_f32_16x16x32_f16 v[100:103], v[148:151], v[246:249], v[100:103]
	v_mfma_f32_16x16x32_f16 v[104:107], v[152:155], v[246:249], v[104:107]
	v_mfma_f32_16x16x32_f16 v[108:111], v[156:159], v[246:249], v[108:111]
	v_mfma_f32_16x16x32_f16 v[112:115], v[160:163], v[246:249], v[112:115]
	v_mfma_f32_16x16x32_f16 v[116:119], v[148:151], v[250:253], v[116:119]
	v_mfma_f32_16x16x32_f16 v[120:123], v[152:155], v[250:253], v[120:123]
	v_mfma_f32_16x16x32_f16 v[124:127], v[156:159], v[250:253], v[124:127]
	v_mfma_f32_16x16x32_f16 v[128:131], v[160:163], v[250:253], v[128:131]
	s_lshl_b64 s[80:81], s[28:29], 13
	s_add_u32 s80, s80, s34
	s_addc_u32 s81, s81, s35
	s_lshl_b32 s82, s65, 1
	s_add_u32 s80, s80, s82
	s_addc_u32 s81, s81, 0
	v_and_b32_e32 v172, 15, v200
	v_bfe_u32 v173, v200, 4, 2
	v_bfe_u32 v174, v200, 6, 2
	v_bfe_u32 v175, v200, 8, 1
	v_lshl_or_b32 v175, v175, 7, v172
	v_lshlrev_b32_e32 v175, 13, v175
	v_lshlrev_b32_e32 v174, 6, v174
	v_lshl_or_b32 v174, v173, 2, v174
	v_lshl_add_u32 v177, v174, 1, v175
	v_and_b32_e32 v172, 1, v173
	v_mul_u32_u24_e32 v172, 24, v172
	v_add_u32_e32 v177, v177, v172
	v_max_f32_e32 v4, 0, v4
	v_max_f32_e32 v5, 0, v5
	v_max_f32_e32 v6, 0, v6
	v_max_f32_e32 v7, 0, v7
	v_pk_mul_f32 v[4:5], v[4:5], v[4:5]
	v_pk_mul_f32 v[6:7], v[6:7], v[6:7]
	v_cvt_pk_f16_f32 v172, v4, v5
	v_cvt_pk_f16_f32 v173, v6, v7
	v_max_f32_e32 v8, 0, v8
	v_max_f32_e32 v9, 0, v9
	v_max_f32_e32 v10, 0, v10
	v_max_f32_e32 v11, 0, v11
	v_pk_mul_f32 v[8:9], v[8:9], v[8:9]
	v_pk_mul_f32 v[10:11], v[10:11], v[10:11]
	v_cvt_pk_f16_f32 v174, v8, v9
	v_cvt_pk_f16_f32 v175, v10, v11
	s_nop 1
	v_permlane16_swap_b32_e32 v172, v174
	v_permlane16_swap_b32_e32 v173, v175
	global_store_dwordx4 v177, v[172:175], s[80:81] nt
	v_max_f32_e32 v12, 0, v12
	v_max_f32_e32 v13, 0, v13
	v_max_f32_e32 v14, 0, v14
	v_max_f32_e32 v15, 0, v15
	v_pk_mul_f32 v[12:13], v[12:13], v[12:13]
	v_pk_mul_f32 v[14:15], v[14:15], v[14:15]
	v_cvt_pk_f16_f32 v228, v12, v13
	v_cvt_pk_f16_f32 v229, v14, v15
	v_max_f32_e32 v16, 0, v16
	v_max_f32_e32 v17, 0, v17
	v_max_f32_e32 v18, 0, v18
	v_max_f32_e32 v19, 0, v19
	v_pk_mul_f32 v[16:17], v[16:17], v[16:17]
	v_pk_mul_f32 v[18:19], v[18:19], v[18:19]
	v_cvt_pk_f16_f32 v230, v16, v17
	v_cvt_pk_f16_f32 v231, v18, v19
	s_nop 1
	v_permlane16_swap_b32_e32 v228, v230
	v_permlane16_swap_b32_e32 v229, v231
	global_store_dwordx4 v177, v[228:231], s[80:81] offset:64 nt
	v_add_u32_e32 v177, 0x20000, v177
	v_max_f32_e32 v20, 0, v20
	v_max_f32_e32 v21, 0, v21
	v_max_f32_e32 v22, 0, v22
	v_max_f32_e32 v23, 0, v23
	v_pk_mul_f32 v[20:21], v[20:21], v[20:21]
	v_pk_mul_f32 v[22:23], v[22:23], v[22:23]
	v_cvt_pk_f16_f32 v172, v20, v21
	v_cvt_pk_f16_f32 v173, v22, v23
	v_max_f32_e32 v24, 0, v24
	v_max_f32_e32 v25, 0, v25
	v_max_f32_e32 v26, 0, v26
	v_max_f32_e32 v27, 0, v27
	v_pk_mul_f32 v[24:25], v[24:25], v[24:25]
	v_pk_mul_f32 v[26:27], v[26:27], v[26:27]
	v_cvt_pk_f16_f32 v174, v24, v25
	v_cvt_pk_f16_f32 v175, v26, v27
	s_nop 1
	v_permlane16_swap_b32_e32 v172, v174
	v_permlane16_swap_b32_e32 v173, v175
	global_store_dwordx4 v177, v[172:175], s[80:81] nt
	v_max_f32_e32 v28, 0, v28
	v_max_f32_e32 v29, 0, v29
	v_max_f32_e32 v30, 0, v30
	v_max_f32_e32 v31, 0, v31
	v_pk_mul_f32 v[28:29], v[28:29], v[28:29]
	v_pk_mul_f32 v[30:31], v[30:31], v[30:31]
	v_cvt_pk_f16_f32 v228, v28, v29
	v_cvt_pk_f16_f32 v229, v30, v31
	v_max_f32_e32 v32, 0, v32
	v_max_f32_e32 v33, 0, v33
	v_max_f32_e32 v34, 0, v34
	v_max_f32_e32 v35, 0, v35
	v_pk_mul_f32 v[32:33], v[32:33], v[32:33]
	v_pk_mul_f32 v[34:35], v[34:35], v[34:35]
	v_cvt_pk_f16_f32 v230, v32, v33
	v_cvt_pk_f16_f32 v231, v34, v35
	s_nop 1
	v_permlane16_swap_b32_e32 v228, v230
	v_permlane16_swap_b32_e32 v229, v231
	global_store_dwordx4 v177, v[228:231], s[80:81] offset:64 nt
	v_add_u32_e32 v177, 0x20000, v177
	v_max_f32_e32 v36, 0, v36
	v_max_f32_e32 v37, 0, v37
	v_max_f32_e32 v38, 0, v38
	v_max_f32_e32 v39, 0, v39
	v_pk_mul_f32 v[36:37], v[36:37], v[36:37]
	v_pk_mul_f32 v[38:39], v[38:39], v[38:39]
	v_cvt_pk_f16_f32 v172, v36, v37
	v_cvt_pk_f16_f32 v173, v38, v39
	v_max_f32_e32 v40, 0, v40
	v_max_f32_e32 v41, 0, v41
	v_max_f32_e32 v42, 0, v42
	v_max_f32_e32 v43, 0, v43
	v_pk_mul_f32 v[40:41], v[40:41], v[40:41]
	v_pk_mul_f32 v[42:43], v[42:43], v[42:43]
	v_cvt_pk_f16_f32 v174, v40, v41
	v_cvt_pk_f16_f32 v175, v42, v43
	s_nop 1
	v_permlane16_swap_b32_e32 v172, v174
	v_permlane16_swap_b32_e32 v173, v175
	global_store_dwordx4 v177, v[172:175], s[80:81] nt
	v_max_f32_e32 v44, 0, v44
	v_max_f32_e32 v45, 0, v45
	v_max_f32_e32 v46, 0, v46
	v_max_f32_e32 v47, 0, v47
	v_pk_mul_f32 v[44:45], v[44:45], v[44:45]
	v_pk_mul_f32 v[46:47], v[46:47], v[46:47]
	v_cvt_pk_f16_f32 v228, v44, v45
	v_cvt_pk_f16_f32 v229, v46, v47
	v_max_f32_e32 v48, 0, v48
	v_max_f32_e32 v49, 0, v49
	v_max_f32_e32 v50, 0, v50
	v_max_f32_e32 v51, 0, v51
	v_pk_mul_f32 v[48:49], v[48:49], v[48:49]
	v_pk_mul_f32 v[50:51], v[50:51], v[50:51]
	v_cvt_pk_f16_f32 v230, v48, v49
	v_cvt_pk_f16_f32 v231, v50, v51
	s_nop 1
	v_permlane16_swap_b32_e32 v228, v230
	v_permlane16_swap_b32_e32 v229, v231
	global_store_dwordx4 v177, v[228:231], s[80:81] offset:64 nt
	v_add_u32_e32 v177, 0x20000, v177
	v_max_f32_e32 v52, 0, v52
	v_max_f32_e32 v53, 0, v53
	v_max_f32_e32 v54, 0, v54
	v_max_f32_e32 v55, 0, v55
	v_pk_mul_f32 v[52:53], v[52:53], v[52:53]
	v_pk_mul_f32 v[54:55], v[54:55], v[54:55]
	v_cvt_pk_f16_f32 v172, v52, v53
	v_cvt_pk_f16_f32 v173, v54, v55
	v_max_f32_e32 v56, 0, v56
	v_max_f32_e32 v57, 0, v57
	v_max_f32_e32 v58, 0, v58
	v_max_f32_e32 v59, 0, v59
	v_pk_mul_f32 v[56:57], v[56:57], v[56:57]
	v_pk_mul_f32 v[58:59], v[58:59], v[58:59]
	v_cvt_pk_f16_f32 v174, v56, v57
	v_cvt_pk_f16_f32 v175, v58, v59
	s_nop 1
	v_permlane16_swap_b32_e32 v172, v174
	v_permlane16_swap_b32_e32 v173, v175
	global_store_dwordx4 v177, v[172:175], s[80:81] nt
	v_max_f32_e32 v60, 0, v60
	v_max_f32_e32 v61, 0, v61
	v_max_f32_e32 v62, 0, v62
	v_max_f32_e32 v63, 0, v63
	v_pk_mul_f32 v[60:61], v[60:61], v[60:61]
	v_pk_mul_f32 v[62:63], v[62:63], v[62:63]
	v_cvt_pk_f16_f32 v228, v60, v61
	v_cvt_pk_f16_f32 v229, v62, v63
	v_max_f32_e32 v64, 0, v64
	v_max_f32_e32 v65, 0, v65
	v_max_f32_e32 v66, 0, v66
	v_max_f32_e32 v67, 0, v67
	v_pk_mul_f32 v[64:65], v[64:65], v[64:65]
	v_pk_mul_f32 v[66:67], v[66:67], v[66:67]
	v_cvt_pk_f16_f32 v230, v64, v65
	v_cvt_pk_f16_f32 v231, v66, v67
	s_nop 1
	v_permlane16_swap_b32_e32 v228, v230
	v_permlane16_swap_b32_e32 v229, v231
	global_store_dwordx4 v177, v[228:231], s[80:81] offset:64 nt
	v_add_u32_e32 v177, 0x20000, v177
	v_max_f32_e32 v68, 0, v68
	v_max_f32_e32 v69, 0, v69
	v_max_f32_e32 v70, 0, v70
	v_max_f32_e32 v71, 0, v71
	v_pk_mul_f32 v[68:69], v[68:69], v[68:69]
	v_pk_mul_f32 v[70:71], v[70:71], v[70:71]
	v_cvt_pk_f16_f32 v172, v68, v69
	v_cvt_pk_f16_f32 v173, v70, v71
	v_max_f32_e32 v72, 0, v72
	v_max_f32_e32 v73, 0, v73
	v_max_f32_e32 v74, 0, v74
	v_max_f32_e32 v75, 0, v75
	v_pk_mul_f32 v[72:73], v[72:73], v[72:73]
	v_pk_mul_f32 v[74:75], v[74:75], v[74:75]
	v_cvt_pk_f16_f32 v174, v72, v73
	v_cvt_pk_f16_f32 v175, v74, v75
	s_nop 1
	v_permlane16_swap_b32_e32 v172, v174
	v_permlane16_swap_b32_e32 v173, v175
	global_store_dwordx4 v177, v[172:175], s[80:81] nt
	v_max_f32_e32 v76, 0, v76
	v_max_f32_e32 v77, 0, v77
	v_max_f32_e32 v78, 0, v78
	v_max_f32_e32 v79, 0, v79
	v_pk_mul_f32 v[76:77], v[76:77], v[76:77]
	v_pk_mul_f32 v[78:79], v[78:79], v[78:79]
	v_cvt_pk_f16_f32 v228, v76, v77
	v_cvt_pk_f16_f32 v229, v78, v79
	v_max_f32_e32 v80, 0, v80
	v_max_f32_e32 v81, 0, v81
	v_max_f32_e32 v82, 0, v82
	v_max_f32_e32 v83, 0, v83
	v_pk_mul_f32 v[80:81], v[80:81], v[80:81]
	v_pk_mul_f32 v[82:83], v[82:83], v[82:83]
	v_cvt_pk_f16_f32 v230, v80, v81
	v_cvt_pk_f16_f32 v231, v82, v83
	s_nop 1
	v_permlane16_swap_b32_e32 v228, v230
	v_permlane16_swap_b32_e32 v229, v231
	global_store_dwordx4 v177, v[228:231], s[80:81] offset:64 nt
	v_add_u32_e32 v177, 0x20000, v177
	v_max_f32_e32 v84, 0, v84
	v_max_f32_e32 v85, 0, v85
	v_max_f32_e32 v86, 0, v86
	v_max_f32_e32 v87, 0, v87
	v_pk_mul_f32 v[84:85], v[84:85], v[84:85]
	v_pk_mul_f32 v[86:87], v[86:87], v[86:87]
	v_cvt_pk_f16_f32 v172, v84, v85
	v_cvt_pk_f16_f32 v173, v86, v87
	v_max_f32_e32 v88, 0, v88
	v_max_f32_e32 v89, 0, v89
	v_max_f32_e32 v90, 0, v90
	v_max_f32_e32 v91, 0, v91
	v_pk_mul_f32 v[88:89], v[88:89], v[88:89]
	v_pk_mul_f32 v[90:91], v[90:91], v[90:91]
	v_cvt_pk_f16_f32 v174, v88, v89
	v_cvt_pk_f16_f32 v175, v90, v91
	s_nop 1
	v_permlane16_swap_b32_e32 v172, v174
	v_permlane16_swap_b32_e32 v173, v175
	global_store_dwordx4 v177, v[172:175], s[80:81] nt
	v_max_f32_e32 v92, 0, v92
	v_max_f32_e32 v93, 0, v93
	v_max_f32_e32 v94, 0, v94
	v_max_f32_e32 v95, 0, v95
	v_pk_mul_f32 v[92:93], v[92:93], v[92:93]
	v_pk_mul_f32 v[94:95], v[94:95], v[94:95]
	v_cvt_pk_f16_f32 v228, v92, v93
	v_cvt_pk_f16_f32 v229, v94, v95
	v_max_f32_e32 v96, 0, v96
	v_max_f32_e32 v97, 0, v97
	v_max_f32_e32 v98, 0, v98
	v_max_f32_e32 v99, 0, v99
	v_pk_mul_f32 v[96:97], v[96:97], v[96:97]
	v_pk_mul_f32 v[98:99], v[98:99], v[98:99]
	v_cvt_pk_f16_f32 v230, v96, v97
	v_cvt_pk_f16_f32 v231, v98, v99
	s_nop 1
	v_permlane16_swap_b32_e32 v228, v230
	v_permlane16_swap_b32_e32 v229, v231
	global_store_dwordx4 v177, v[228:231], s[80:81] offset:64 nt
	v_add_u32_e32 v177, 0x20000, v177
	v_max_f32_e32 v100, 0, v100
	v_max_f32_e32 v101, 0, v101
	v_max_f32_e32 v102, 0, v102
	v_max_f32_e32 v103, 0, v103
	v_pk_mul_f32 v[100:101], v[100:101], v[100:101]
	v_pk_mul_f32 v[102:103], v[102:103], v[102:103]
	v_cvt_pk_f16_f32 v172, v100, v101
	v_cvt_pk_f16_f32 v173, v102, v103
	v_max_f32_e32 v104, 0, v104
	v_max_f32_e32 v105, 0, v105
	v_max_f32_e32 v106, 0, v106
	v_max_f32_e32 v107, 0, v107
	v_pk_mul_f32 v[104:105], v[104:105], v[104:105]
	v_pk_mul_f32 v[106:107], v[106:107], v[106:107]
	v_cvt_pk_f16_f32 v174, v104, v105
	v_cvt_pk_f16_f32 v175, v106, v107
	s_nop 1
	v_permlane16_swap_b32_e32 v172, v174
	v_permlane16_swap_b32_e32 v173, v175
	global_store_dwordx4 v177, v[172:175], s[80:81] nt
	v_max_f32_e32 v108, 0, v108
	v_max_f32_e32 v109, 0, v109
	v_max_f32_e32 v110, 0, v110
	v_max_f32_e32 v111, 0, v111
	v_pk_mul_f32 v[108:109], v[108:109], v[108:109]
	v_pk_mul_f32 v[110:111], v[110:111], v[110:111]
	v_cvt_pk_f16_f32 v228, v108, v109
	v_cvt_pk_f16_f32 v229, v110, v111
	v_max_f32_e32 v112, 0, v112
	v_max_f32_e32 v113, 0, v113
	v_max_f32_e32 v114, 0, v114
	v_max_f32_e32 v115, 0, v115
	v_pk_mul_f32 v[112:113], v[112:113], v[112:113]
	v_pk_mul_f32 v[114:115], v[114:115], v[114:115]
	v_cvt_pk_f16_f32 v230, v112, v113
	v_cvt_pk_f16_f32 v231, v114, v115
	s_nop 1
	v_permlane16_swap_b32_e32 v228, v230
	v_permlane16_swap_b32_e32 v229, v231
	global_store_dwordx4 v177, v[228:231], s[80:81] offset:64 nt
	v_add_u32_e32 v177, 0x20000, v177
	v_max_f32_e32 v116, 0, v116
	v_max_f32_e32 v117, 0, v117
	v_max_f32_e32 v118, 0, v118
	v_max_f32_e32 v119, 0, v119
	v_pk_mul_f32 v[116:117], v[116:117], v[116:117]
	v_pk_mul_f32 v[118:119], v[118:119], v[118:119]
	v_cvt_pk_f16_f32 v172, v116, v117
	v_cvt_pk_f16_f32 v173, v118, v119
	v_max_f32_e32 v120, 0, v120
	v_max_f32_e32 v121, 0, v121
	v_max_f32_e32 v122, 0, v122
	v_max_f32_e32 v123, 0, v123
	v_pk_mul_f32 v[120:121], v[120:121], v[120:121]
	v_pk_mul_f32 v[122:123], v[122:123], v[122:123]
	v_cvt_pk_f16_f32 v174, v120, v121
	v_cvt_pk_f16_f32 v175, v122, v123
	s_nop 1
	v_permlane16_swap_b32_e32 v172, v174
	v_permlane16_swap_b32_e32 v173, v175
	global_store_dwordx4 v177, v[172:175], s[80:81] nt
	v_max_f32_e32 v124, 0, v124
	v_max_f32_e32 v125, 0, v125
	v_max_f32_e32 v126, 0, v126
	v_max_f32_e32 v127, 0, v127
	v_pk_mul_f32 v[124:125], v[124:125], v[124:125]
	v_pk_mul_f32 v[126:127], v[126:127], v[126:127]
	v_cvt_pk_f16_f32 v228, v124, v125
	v_cvt_pk_f16_f32 v229, v126, v127
	v_max_f32_e32 v128, 0, v128
	v_max_f32_e32 v129, 0, v129
	v_max_f32_e32 v130, 0, v130
	v_max_f32_e32 v131, 0, v131
	v_pk_mul_f32 v[128:129], v[128:129], v[128:129]
	v_pk_mul_f32 v[130:131], v[130:131], v[130:131]
	v_cvt_pk_f16_f32 v230, v128, v129
	v_cvt_pk_f16_f32 v231, v130, v131
	s_nop 1
	v_permlane16_swap_b32_e32 v228, v230
	v_permlane16_swap_b32_e32 v229, v231
	global_store_dwordx4 v177, v[228:231], s[80:81] offset:64 nt
	s_nop 1
	s_add_i32 s54, s54, s76
	s_cmp_ge_i32 s54, s58
	s_cbranch_scc1 .LBB0_780
	s_branch .LBB0_725

.Lt_gin:
	v_add_u32_e32 v169, s47, v164
	v_mfma_f32_16x16x32_f16 v[4:7], v[132:135], v[184:187], v[4:7]
	ds_read_b128 v[238:241], v169 offset:4112
	v_mfma_f32_16x16x32_f16 v[8:11], v[136:139], v[184:187], v[8:11]
	ds_read_b128 v[242:245], v169 offset:5136
	v_mfma_f32_16x16x32_f16 v[12:15], v[140:143], v[184:187], v[12:15]
	ds_read_b128 v[246:249], v169 offset:6160
	v_mfma_f32_16x16x32_f16 v[16:19], v[144:147], v[184:187], v[16:19]
	ds_read_b128 v[250:253], v169 offset:7184
	v_mfma_f32_16x16x32_f16 v[20:23], v[132:135], v[188:191], v[20:23]
	v_mfma_f32_16x16x32_f16 v[24:27], v[136:139], v[188:191], v[24:27]
	v_mfma_f32_16x16x32_f16 v[28:31], v[140:143], v[188:191], v[28:31]
	v_mfma_f32_16x16x32_f16 v[32:35], v[144:147], v[188:191], v[32:35]
	v_mfma_f32_16x16x32_f16 v[36:39], v[132:135], v[192:195], v[36:39]
	v_mfma_f32_16x16x32_f16 v[40:43], v[136:139], v[192:195], v[40:43]
	v_mfma_f32_16x16x32_f16 v[44:47], v[140:143], v[192:195], v[44:47]
	v_mfma_f32_16x16x32_f16 v[48:51], v[144:147], v[192:195], v[48:51]
	v_mfma_f32_16x16x32_f16 v[52:55], v[132:135], v[196:199], v[52:55]
	v_mfma_f32_16x16x32_f16 v[56:59], v[136:139], v[196:199], v[56:59]
	v_mfma_f32_16x16x32_f16 v[60:63], v[140:143], v[196:199], v[60:63]
	v_mfma_f32_16x16x32_f16 v[64:67], v[144:147], v[196:199], v[64:67]
	s_waitcnt vmcnt(8) lgkmcnt(0)
	s_barrier
	s_add_i32 s48, s47, 0x8000
	s_cmp_lg_u32 s47, 0x18000
	s_cselect_b32 s48, s48, 0
	v_add_u32_e32 v168, s48, v165
	v_add_u32_e32 v169, s48, v164
	s_add_u32 vcc_lo, s32, s47
	v_mfma_f32_16x16x32_f16 v[68:71], v[132:135], v[238:241], v[68:71]
	ds_read_b128 v[148:151], v168 offset:16
	ds_read_b128 v[184:187], v169 offset:16
	v_mfma_f32_16x16x32_f16 v[72:75], v[136:139], v[238:241], v[72:75]
	ds_read_b128 v[152:155], v168 offset:1040
	ds_read_b128 v[188:191], v169 offset:1040
	v_mfma_f32_16x16x32_f16 v[76:79], v[140:143], v[238:241], v[76:79]
	ds_read_b128 v[156:159], v168 offset:2064
	ds_read_b128 v[192:195], v169 offset:2064
	v_mfma_f32_16x16x32_f16 v[80:83], v[144:147], v[238:241], v[80:83]
	ds_read_b128 v[160:163], v168 offset:3088
	ds_read_b128 v[196:199], v169 offset:3088
	v_mfma_f32_16x16x32_f16 v[84:87], v[132:135], v[242:245], v[84:87]
	v_mfma_f32_16x16x32_f16 v[88:91], v[136:139], v[242:245], v[88:91]
	v_mfma_f32_16x16x32_f16 v[92:95], v[140:143], v[242:245], v[92:95]
	v_mfma_f32_16x16x32_f16 v[96:99], v[144:147], v[242:245], v[96:99]
	v_mfma_f32_16x16x32_f16 v[100:103], v[132:135], v[246:249], v[100:103]
	s_mov_b32 m0, vcc_lo
	s_nop 0
	global_load_lds_dwordx4 v170, s[36:37]
	v_mfma_f32_16x16x32_f16 v[104:107], v[136:139], v[246:249], v[104:107]
	s_add_u32 m0, vcc_lo, 0x400
	s_nop 0
	global_load_lds_dwordx4 v171, s[36:37]
	v_mfma_f32_16x16x32_f16 v[108:111], v[140:143], v[246:249], v[108:111]
	s_add_u32 m0, vcc_lo, 0x4000
	s_nop 0
	global_load_lds_dwordx4 v170, s[42:43]
	v_mfma_f32_16x16x32_f16 v[112:115], v[144:147], v[246:249], v[112:115]
	s_add_u32 m0, vcc_lo, 0x4400
	s_nop 0
	global_load_lds_dwordx4 v171, s[42:43]
	v_mfma_f32_16x16x32_f16 v[116:119], v[132:135], v[250:253], v[116:119]
	v_mfma_f32_16x16x32_f16 v[120:123], v[136:139], v[250:253], v[120:123]
	v_mfma_f32_16x16x32_f16 v[124:127], v[140:143], v[250:253], v[124:127]
	v_mfma_f32_16x16x32_f16 v[128:131], v[144:147], v[250:253], v[128:131]
	s_waitcnt lgkmcnt(0)
	s_mov_b32 s47, s48
	s_add_u32 s36, s36, 64
	s_addc_u32 s37, s37, 0
	s_add_u32 s42, s42, 64
	s_addc_u32 s43, s43, 0
	v_add_u32_e32 v169, s47, v164
	v_mfma_f32_16x16x32_f16 v[4:7], v[148:151], v[184:187], v[4:7]
	ds_read_b128 v[238:241], v169 offset:4112
	v_mfma_f32_16x16x32_f16 v[8:11], v[152:155], v[184:187], v[8:11]
	ds_read_b128 v[242:245], v169 offset:5136
	v_mfma_f32_16x16x32_f16 v[12:15], v[156:159], v[184:187], v[12:15]
	ds_read_b128 v[246:249], v169 offset:6160
	v_mfma_f32_16x16x32_f16 v[16:19], v[160:163], v[184:187], v[16:19]
	ds_read_b128 v[250:253], v169 offset:7184
	v_mfma_f32_16x16x32_f16 v[20:23], v[148:151], v[188:191], v[20:23]
	v_mfma_f32_16x16x32_f16 v[24:27], v[152:155], v[188:191], v[24:27]
	v_mfma_f32_16x16x32_f16 v[28:31], v[156:159], v[188:191], v[28:31]
	v_mfma_f32_16x16x32_f16 v[32:35], v[160:163], v[188:191], v[32:35]
	v_mfma_f32_16x16x32_f16 v[36:39], v[148:151], v[192:195], v[36:39]
	v_mfma_f32_16x16x32_f16 v[40:43], v[152:155], v[192:195], v[40:43]
	v_mfma_f32_16x16x32_f16 v[44:47], v[156:159], v[192:195], v[44:47]
	v_mfma_f32_16x16x32_f16 v[48:51], v[160:163], v[192:195], v[48:51]
	v_mfma_f32_16x16x32_f16 v[52:55], v[148:151], v[196:199], v[52:55]
	v_mfma_f32_16x16x32_f16 v[56:59], v[152:155], v[196:199], v[56:59]
	v_mfma_f32_16x16x32_f16 v[60:63], v[156:159], v[196:199], v[60:63]
	v_mfma_f32_16x16x32_f16 v[64:67], v[160:163], v[196:199], v[64:67]
	s_waitcnt vmcnt(8) lgkmcnt(0)
	s_barrier
	s_add_i32 s48, s47, 0x8000
	s_cmp_lg_u32 s47, 0x18000
	s_cselect_b32 s48, s48, 0
	v_add_u32_e32 v168, s48, v165
	v_add_u32_e32 v169, s48, v164
	s_add_u32 vcc_lo, s32, s47
	v_mfma_f32_16x16x32_f16 v[68:71], v[148:151], v[238:241], v[68:71]
	ds_read_b128 v[132:135], v168 offset:16
	ds_read_b128 v[184:187], v169 offset:16
	v_mfma_f32_16x16x32_f16 v[72:75], v[152:155], v[238:241], v[72:75]
	ds_read_b128 v[136:139], v168 offset:1040
	ds_read_b128 v[188:191], v169 offset:1040
	v_mfma_f32_16x16x32_f16 v[76:79], v[156:159], v[238:241], v[76:79]
	ds_read_b128 v[140:143], v168 offset:2064
	ds_read_b128 v[192:195], v169 offset:2064
	v_mfma_f32_16x16x32_f16 v[80:83], v[160:163], v[238:241], v[80:83]
	ds_read_b128 v[144:147], v168 offset:3088
	ds_read_b128 v[196:199], v169 offset:3088
	v_mfma_f32_16x16x32_f16 v[84:87], v[148:151], v[242:245], v[84:87]
	v_mfma_f32_16x16x32_f16 v[88:91], v[152:155], v[242:245], v[88:91]
	v_mfma_f32_16x16x32_f16 v[92:95], v[156:159], v[242:245], v[92:95]
	v_mfma_f32_16x16x32_f16 v[96:99], v[160:163], v[242:245], v[96:99]
	v_mfma_f32_16x16x32_f16 v[100:103], v[148:151], v[246:249], v[100:103]
	s_mov_b32 m0, vcc_lo
	s_nop 0
	global_load_lds_dwordx4 v170, s[36:37]
	v_mfma_f32_16x16x32_f16 v[104:107], v[152:155], v[246:249], v[104:107]
	s_add_u32 m0, vcc_lo, 0x400
	s_nop 0
	global_load_lds_dwordx4 v171, s[36:37]
	v_mfma_f32_16x16x32_f16 v[108:111], v[156:159], v[246:249], v[108:111]
	s_add_u32 m0, vcc_lo, 0x4000
	s_nop 0
	global_load_lds_dwordx4 v170, s[42:43]
	v_mfma_f32_16x16x32_f16 v[112:115], v[160:163], v[246:249], v[112:115]
	s_add_u32 m0, vcc_lo, 0x4400
	s_nop 0
	global_load_lds_dwordx4 v171, s[42:43]
	v_mfma_f32_16x16x32_f16 v[116:119], v[148:151], v[250:253], v[116:119]
	v_mfma_f32_16x16x32_f16 v[120:123], v[152:155], v[250:253], v[120:123]
	v_mfma_f32_16x16x32_f16 v[124:127], v[156:159], v[250:253], v[124:127]
	v_mfma_f32_16x16x32_f16 v[128:131], v[160:163], v[250:253], v[128:131]
	s_waitcnt lgkmcnt(0)
	s_mov_b32 s47, s48
	s_add_u32 s36, s36, 64
	s_addc_u32 s37, s37, 0
	s_add_u32 s42, s42, 64
	s_addc_u32 s43, s43, 0
	s_add_i32 s49, s49, 2
	s_cmp_lt_u32 s49, 28
	s_cbranch_scc1 .Lt_gin
	v_add_u32_e32 v169, s47, v164
	v_mfma_f32_16x16x32_f16 v[4:7], v[132:135], v[184:187], v[4:7]
	ds_read_b128 v[238:241], v169 offset:4112
	v_mfma_f32_16x16x32_f16 v[8:11], v[136:139], v[184:187], v[8:11]
	ds_read_b128 v[242:245], v169 offset:5136
	v_mfma_f32_16x16x32_f16 v[12:15], v[140:143], v[184:187], v[12:15]
	ds_read_b128 v[246:249], v169 offset:6160
	v_mfma_f32_16x16x32_f16 v[16:19], v[144:147], v[184:187], v[16:19]
	ds_read_b128 v[250:253], v169 offset:7184
	v_mfma_f32_16x16x32_f16 v[20:23], v[132:135], v[188:191], v[20:23]
	v_mfma_f32_16x16x32_f16 v[24:27], v[136:139], v[188:191], v[24:27]
	v_mfma_f32_16x16x32_f16 v[28:31], v[140:143], v[188:191], v[28:31]
	v_mfma_f32_16x16x32_f16 v[32:35], v[144:147], v[188:191], v[32:35]
	v_mfma_f32_16x16x32_f16 v[36:39], v[132:135], v[192:195], v[36:39]
	v_mfma_f32_16x16x32_f16 v[40:43], v[136:139], v[192:195], v[40:43]
	v_mfma_f32_16x16x32_f16 v[44:47], v[140:143], v[192:195], v[44:47]
	v_mfma_f32_16x16x32_f16 v[48:51], v[144:147], v[192:195], v[48:51]
	v_mfma_f32_16x16x32_f16 v[52:55], v[132:135], v[196:199], v[52:55]
	v_mfma_f32_16x16x32_f16 v[56:59], v[136:139], v[196:199], v[56:59]
	v_mfma_f32_16x16x32_f16 v[60:63], v[140:143], v[196:199], v[60:63]
	v_mfma_f32_16x16x32_f16 v[64:67], v[144:147], v[196:199], v[64:67]
	s_waitcnt vmcnt(8) lgkmcnt(0)
	s_barrier
	s_add_i32 s48, s47, 0x8000
	s_cmp_lg_u32 s47, 0x18000
	s_cselect_b32 s48, s48, 0
	v_add_u32_e32 v168, s48, v165
	v_add_u32_e32 v169, s48, v164
	v_mfma_f32_16x16x32_f16 v[68:71], v[132:135], v[238:241], v[68:71]
	ds_read_b128 v[148:151], v168 offset:16
	ds_read_b128 v[184:187], v169 offset:16
	v_mfma_f32_16x16x32_f16 v[72:75], v[136:139], v[238:241], v[72:75]
	ds_read_b128 v[152:155], v168 offset:1040
	ds_read_b128 v[188:191], v169 offset:1040
	v_mfma_f32_16x16x32_f16 v[76:79], v[140:143], v[238:241], v[76:79]
	ds_read_b128 v[156:159], v168 offset:2064
	ds_read_b128 v[192:195], v169 offset:2064
	v_mfma_f32_16x16x32_f16 v[80:83], v[144:147], v[238:241], v[80:83]
	ds_read_b128 v[160:163], v168 offset:3088
	ds_read_b128 v[196:199], v169 offset:3088
	v_mfma_f32_16x16x32_f16 v[84:87], v[132:135], v[242:245], v[84:87]
	v_mfma_f32_16x16x32_f16 v[88:91], v[136:139], v[242:245], v[88:91]
	v_mfma_f32_16x16x32_f16 v[92:95], v[140:143], v[242:245], v[92:95]
	v_mfma_f32_16x16x32_f16 v[96:99], v[144:147], v[242:245], v[96:99]
	v_mfma_f32_16x16x32_f16 v[100:103], v[132:135], v[246:249], v[100:103]
	v_mfma_f32_16x16x32_f16 v[104:107], v[136:139], v[246:249], v[104:107]
	v_mfma_f32_16x16x32_f16 v[108:111], v[140:143], v[246:249], v[108:111]
	v_mfma_f32_16x16x32_f16 v[112:115], v[144:147], v[246:249], v[112:115]
	v_mfma_f32_16x16x32_f16 v[116:119], v[132:135], v[250:253], v[116:119]
	v_mfma_f32_16x16x32_f16 v[120:123], v[136:139], v[250:253], v[120:123]
	v_mfma_f32_16x16x32_f16 v[124:127], v[140:143], v[250:253], v[124:127]
	v_mfma_f32_16x16x32_f16 v[128:131], v[144:147], v[250:253], v[128:131]
	s_waitcnt lgkmcnt(0)
	s_mov_b32 s47, s48
	v_add_u32_e32 v169, s47, v164
	v_mfma_f32_16x16x32_f16 v[4:7], v[148:151], v[184:187], v[4:7]
	ds_read_b128 v[238:241], v169 offset:4112
	v_mfma_f32_16x16x32_f16 v[8:11], v[152:155], v[184:187], v[8:11]
	ds_read_b128 v[242:245], v169 offset:5136
	v_mfma_f32_16x16x32_f16 v[12:15], v[156:159], v[184:187], v[12:15]
	ds_read_b128 v[246:249], v169 offset:6160
	v_mfma_f32_16x16x32_f16 v[16:19], v[160:163], v[184:187], v[16:19]
	ds_read_b128 v[250:253], v169 offset:7184
	v_mfma_f32_16x16x32_f16 v[20:23], v[148:151], v[188:191], v[20:23]
	v_mfma_f32_16x16x32_f16 v[24:27], v[152:155], v[188:191], v[24:27]
	v_mfma_f32_16x16x32_f16 v[28:31], v[156:159], v[188:191], v[28:31]
	v_mfma_f32_16x16x32_f16 v[32:35], v[160:163], v[188:191], v[32:35]
	v_mfma_f32_16x16x32_f16 v[36:39], v[148:151], v[192:195], v[36:39]
	v_mfma_f32_16x16x32_f16 v[40:43], v[152:155], v[192:195], v[40:43]
	v_mfma_f32_16x16x32_f16 v[44:47], v[156:159], v[192:195], v[44:47]
	v_mfma_f32_16x16x32_f16 v[48:51], v[160:163], v[192:195], v[48:51]
	v_mfma_f32_16x16x32_f16 v[52:55], v[148:151], v[196:199], v[52:55]
	v_mfma_f32_16x16x32_f16 v[56:59], v[152:155], v[196:199], v[56:59]
	v_mfma_f32_16x16x32_f16 v[60:63], v[156:159], v[196:199], v[60:63]
	v_mfma_f32_16x16x32_f16 v[64:67], v[160:163], v[196:199], v[64:67]
	s_waitcnt vmcnt(4) lgkmcnt(0)
	s_barrier
	s_add_i32 s48, s47, 0x8000
	s_cmp_lg_u32 s47, 0x18000
	s_cselect_b32 s48, s48, 0
	v_add_u32_e32 v168, s48, v165
	v_add_u32_e32 v169, s48, v164
	v_mfma_f32_16x16x32_f16 v[68:71], v[148:151], v[238:241], v[68:71]
	ds_read_b128 v[132:135], v168 offset:16
	ds_read_b128 v[184:187], v169 offset:16
	v_mfma_f32_16x16x32_f16 v[72:75], v[152:155], v[238:241], v[72:75]
	ds_read_b128 v[136:139], v168 offset:1040
	ds_read_b128 v[188:191], v169 offset:1040
	v_mfma_f32_16x16x32_f16 v[76:79], v[156:159], v[238:241], v[76:79]
	ds_read_b128 v[140:143], v168 offset:2064
	ds_read_b128 v[192:195], v169 offset:2064
	v_mfma_f32_16x16x32_f16 v[80:83], v[160:163], v[238:241], v[80:83]
	ds_read_b128 v[144:147], v168 offset:3088
	ds_read_b128 v[196:199], v169 offset:3088
	v_mfma_f32_16x16x32_f16 v[84:87], v[148:151], v[242:245], v[84:87]
	v_mfma_f32_16x16x32_f16 v[88:91], v[152:155], v[242:245], v[88:91]
	v_mfma_f32_16x16x32_f16 v[92:95], v[156:159], v[242:245], v[92:95]
	v_mfma_f32_16x16x32_f16 v[96:99], v[160:163], v[242:245], v[96:99]
	v_mfma_f32_16x16x32_f16 v[100:103], v[148:151], v[246:249], v[100:103]
	v_mfma_f32_16x16x32_f16 v[104:107], v[152:155], v[246:249], v[104:107]
	v_mfma_f32_16x16x32_f16 v[108:111], v[156:159], v[246:249], v[108:111]
	v_mfma_f32_16x16x32_f16 v[112:115], v[160:163], v[246:249], v[112:115]
	v_mfma_f32_16x16x32_f16 v[116:119], v[148:151], v[250:253], v[116:119]
	v_mfma_f32_16x16x32_f16 v[120:123], v[152:155], v[250:253], v[120:123]
	v_mfma_f32_16x16x32_f16 v[124:127], v[156:159], v[250:253], v[124:127]
	v_mfma_f32_16x16x32_f16 v[128:131], v[160:163], v[250:253], v[128:131]
	s_waitcnt lgkmcnt(0)
	s_mov_b32 s47, s48
	v_add_u32_e32 v169, s47, v164
	v_mfma_f32_16x16x32_f16 v[4:7], v[132:135], v[184:187], v[4:7]
	ds_read_b128 v[238:241], v169 offset:4112
	v_mfma_f32_16x16x32_f16 v[8:11], v[136:139], v[184:187], v[8:11]
	ds_read_b128 v[242:245], v169 offset:5136
	v_mfma_f32_16x16x32_f16 v[12:15], v[140:143], v[184:187], v[12:15]
	ds_read_b128 v[246:249], v169 offset:6160
	v_mfma_f32_16x16x32_f16 v[16:19], v[144:147], v[184:187], v[16:19]
	ds_read_b128 v[250:253], v169 offset:7184
	v_mfma_f32_16x16x32_f16 v[20:23], v[132:135], v[188:191], v[20:23]
	v_mfma_f32_16x16x32_f16 v[24:27], v[136:139], v[188:191], v[24:27]
	v_mfma_f32_16x16x32_f16 v[28:31], v[140:143], v[188:191], v[28:31]
	v_mfma_f32_16x16x32_f16 v[32:35], v[144:147], v[188:191], v[32:35]
	v_mfma_f32_16x16x32_f16 v[36:39], v[132:135], v[192:195], v[36:39]
	v_mfma_f32_16x16x32_f16 v[40:43], v[136:139], v[192:195], v[40:43]
	v_mfma_f32_16x16x32_f16 v[44:47], v[140:143], v[192:195], v[44:47]
	v_mfma_f32_16x16x32_f16 v[48:51], v[144:147], v[192:195], v[48:51]
	v_mfma_f32_16x16x32_f16 v[52:55], v[132:135], v[196:199], v[52:55]
	v_mfma_f32_16x16x32_f16 v[56:59], v[136:139], v[196:199], v[56:59]
	v_mfma_f32_16x16x32_f16 v[60:63], v[140:143], v[196:199], v[60:63]
	v_mfma_f32_16x16x32_f16 v[64:67], v[144:147], v[196:199], v[64:67]
	s_waitcnt vmcnt(0) lgkmcnt(0)
	s_barrier
	s_add_i32 s48, s47, 0x8000
	s_cmp_lg_u32 s47, 0x18000
	s_cselect_b32 s48, s48, 0
	v_add_u32_e32 v168, s48, v165
	v_add_u32_e32 v169, s48, v164
	v_mfma_f32_16x16x32_f16 v[68:71], v[132:135], v[238:241], v[68:71]
	ds_read_b128 v[148:151], v168 offset:16
	ds_read_b128 v[184:187], v169 offset:16
	v_mfma_f32_16x16x32_f16 v[72:75], v[136:139], v[238:241], v[72:75]
	ds_read_b128 v[152:155], v168 offset:1040
	ds_read_b128 v[188:191], v169 offset:1040
	v_mfma_f32_16x16x32_f16 v[76:79], v[140:143], v[238:241], v[76:79]
	ds_read_b128 v[156:159], v168 offset:2064
	ds_read_b128 v[192:195], v169 offset:2064
	v_mfma_f32_16x16x32_f16 v[80:83], v[144:147], v[238:241], v[80:83]
	ds_read_b128 v[160:163], v168 offset:3088
	ds_read_b128 v[196:199], v169 offset:3088
	v_mfma_f32_16x16x32_f16 v[84:87], v[132:135], v[242:245], v[84:87]
	v_mfma_f32_16x16x32_f16 v[88:91], v[136:139], v[242:245], v[88:91]
	v_mfma_f32_16x16x32_f16 v[92:95], v[140:143], v[242:245], v[92:95]
	v_mfma_f32_16x16x32_f16 v[96:99], v[144:147], v[242:245], v[96:99]
	v_mfma_f32_16x16x32_f16 v[100:103], v[132:135], v[246:249], v[100:103]
	v_mfma_f32_16x16x32_f16 v[104:107], v[136:139], v[246:249], v[104:107]
	v_mfma_f32_16x16x32_f16 v[108:111], v[140:143], v[246:249], v[108:111]
	v_mfma_f32_16x16x32_f16 v[112:115], v[144:147], v[246:249], v[112:115]
	v_mfma_f32_16x16x32_f16 v[116:119], v[132:135], v[250:253], v[116:119]
	v_mfma_f32_16x16x32_f16 v[120:123], v[136:139], v[250:253], v[120:123]
	v_mfma_f32_16x16x32_f16 v[124:127], v[140:143], v[250:253], v[124:127]
	v_mfma_f32_16x16x32_f16 v[128:131], v[144:147], v[250:253], v[128:131]
	s_waitcnt lgkmcnt(0)
	s_mov_b32 s47, s48
	v_add_u32_e32 v169, s47, v164
	v_mfma_f32_16x16x32_f16 v[4:7], v[148:151], v[184:187], v[4:7]
	ds_read_b128 v[238:241], v169 offset:4112
	v_mfma_f32_16x16x32_f16 v[8:11], v[152:155], v[184:187], v[8:11]
	ds_read_b128 v[242:245], v169 offset:5136
	v_mfma_f32_16x16x32_f16 v[12:15], v[156:159], v[184:187], v[12:15]
	ds_read_b128 v[246:249], v169 offset:6160
	v_mfma_f32_16x16x32_f16 v[16:19], v[160:163], v[184:187], v[16:19]
	ds_read_b128 v[250:253], v169 offset:7184
	v_mfma_f32_16x16x32_f16 v[20:23], v[148:151], v[188:191], v[20:23]
	v_mfma_f32_16x16x32_f16 v[24:27], v[152:155], v[188:191], v[24:27]
	v_mfma_f32_16x16x32_f16 v[28:31], v[156:159], v[188:191], v[28:31]
	v_mfma_f32_16x16x32_f16 v[32:35], v[160:163], v[188:191], v[32:35]
	v_mfma_f32_16x16x32_f16 v[36:39], v[148:151], v[192:195], v[36:39]
	v_mfma_f32_16x16x32_f16 v[40:43], v[152:155], v[192:195], v[40:43]
	v_mfma_f32_16x16x32_f16 v[44:47], v[156:159], v[192:195], v[44:47]
	v_mfma_f32_16x16x32_f16 v[48:51], v[160:163], v[192:195], v[48:51]
	v_mfma_f32_16x16x32_f16 v[52:55], v[148:151], v[196:199], v[52:55]
	v_mfma_f32_16x16x32_f16 v[56:59], v[152:155], v[196:199], v[56:59]
	v_mfma_f32_16x16x32_f16 v[60:63], v[156:159], v[196:199], v[60:63]
	v_mfma_f32_16x16x32_f16 v[64:67], v[160:163], v[196:199], v[64:67]
	s_waitcnt lgkmcnt(0)
	s_barrier
	v_mfma_f32_16x16x32_f16 v[68:71], v[148:151], v[238:241], v[68:71]
	v_mfma_f32_16x16x32_f16 v[72:75], v[152:155], v[238:241], v[72:75]
	v_mfma_f32_16x16x32_f16 v[76:79], v[156:159], v[238:241], v[76:79]
	v_mfma_f32_16x16x32_f16 v[80:83], v[160:163], v[238:241], v[80:83]
	v_mfma_f32_16x16x32_f16 v[84:87], v[148:151], v[242:245], v[84:87]
	v_mfma_f32_16x16x32_f16 v[88:91], v[152:155], v[242:245], v[88:91]
	v_mfma_f32_16x16x32_f16 v[92:95], v[156:159], v[242:245], v[92:95]
	v_mfma_f32_16x16x32_f16 v[96:99], v[160:163], v[242:245], v[96:99]
	v_mfma_f32_16x16x32_f16 v[100:103], v[148:151], v[246:249], v[100:103]
	v_mfma_f32_16x16x32_f16 v[104:107], v[152:155], v[246:249], v[104:107]
	v_mfma_f32_16x16x32_f16 v[108:111], v[156:159], v[246:249], v[108:111]
	v_mfma_f32_16x16x32_f16 v[112:115], v[160:163], v[246:249], v[112:115]
	v_mfma_f32_16x16x32_f16 v[116:119], v[148:151], v[250:253], v[116:119]
	v_mfma_f32_16x16x32_f16 v[120:123], v[152:155], v[250:253], v[120:123]
	v_mfma_f32_16x16x32_f16 v[124:127], v[156:159], v[250:253], v[124:127]
	v_mfma_f32_16x16x32_f16 v[128:131], v[160:163], v[250:253], v[128:131]
	s_mul_i32 s82, s52, 0xc00
	s_add_u32 s80, s28, s82
	s_addc_u32 s81, s29, 0
	s_lshl_b32 s82, s51, 1
	s_add_u32 s80, s80, s82
	s_addc_u32 s81, s81, 0
	v_and_b32_e32 v172, 15, v200
	v_bfe_u32 v173, v200, 4, 2
	v_bfe_u32 v174, v200, 6, 2
	v_bfe_u32 v175, v200, 8, 1
	v_lshl_or_b32 v175, v175, 7, v172
	v_mul_u32_u24_e32 v175, 0xc00, v175
	v_lshlrev_b32_e32 v174, 6, v174
	v_lshl_or_b32 v174, v173, 2, v174
	v_lshl_add_u32 v177, v174, 1, v175
	v_and_b32_e32 v172, 1, v173
	v_mul_u32_u24_e32 v172, 24, v172
	v_add_u32_e32 v177, v177, v172
	v_cvt_pk_f16_f32 v172, v4, v5
	v_cvt_pk_f16_f32 v173, v6, v7
	v_cvt_pk_f16_f32 v174, v8, v9
	v_cvt_pk_f16_f32 v175, v10, v11
	s_nop 1
	v_permlane16_swap_b32_e32 v172, v174
	v_permlane16_swap_b32_e32 v173, v175
	global_store_dwordx4 v177, v[172:175], s[80:81] nt
	v_cvt_pk_f16_f32 v228, v12, v13
	v_cvt_pk_f16_f32 v229, v14, v15
	v_cvt_pk_f16_f32 v230, v16, v17
	v_cvt_pk_f16_f32 v231, v18, v19
	s_nop 1
	v_permlane16_swap_b32_e32 v228, v230
	v_permlane16_swap_b32_e32 v229, v231
	global_store_dwordx4 v177, v[228:231], s[80:81] offset:64 nt
	v_add_u32_e32 v177, 0xc000, v177
	v_cvt_pk_f16_f32 v172, v20, v21
	v_cvt_pk_f16_f32 v173, v22, v23
	v_cvt_pk_f16_f32 v174, v24, v25
	v_cvt_pk_f16_f32 v175, v26, v27
	s_nop 1
	v_permlane16_swap_b32_e32 v172, v174
	v_permlane16_swap_b32_e32 v173, v175
	global_store_dwordx4 v177, v[172:175], s[80:81] nt
	v_cvt_pk_f16_f32 v228, v28, v29
	v_cvt_pk_f16_f32 v229, v30, v31
	v_cvt_pk_f16_f32 v230, v32, v33
	v_cvt_pk_f16_f32 v231, v34, v35
	s_nop 1
	v_permlane16_swap_b32_e32 v228, v230
	v_permlane16_swap_b32_e32 v229, v231
	global_store_dwordx4 v177, v[228:231], s[80:81] offset:64 nt
	v_add_u32_e32 v177, 0xc000, v177
	v_cvt_pk_f16_f32 v172, v36, v37
	v_cvt_pk_f16_f32 v173, v38, v39
	v_cvt_pk_f16_f32 v174, v40, v41
	v_cvt_pk_f16_f32 v175, v42, v43
	s_nop 1
	v_permlane16_swap_b32_e32 v172, v174
	v_permlane16_swap_b32_e32 v173, v175
	global_store_dwordx4 v177, v[172:175], s[80:81] nt
	v_cvt_pk_f16_f32 v228, v44, v45
	v_cvt_pk_f16_f32 v229, v46, v47
	v_cvt_pk_f16_f32 v230, v48, v49
	v_cvt_pk_f16_f32 v231, v50, v51
	s_nop 1
	v_permlane16_swap_b32_e32 v228, v230
	v_permlane16_swap_b32_e32 v229, v231
	global_store_dwordx4 v177, v[228:231], s[80:81] offset:64 nt
	v_add_u32_e32 v177, 0xc000, v177
	v_cvt_pk_f16_f32 v172, v52, v53
	v_cvt_pk_f16_f32 v173, v54, v55
	v_cvt_pk_f16_f32 v174, v56, v57
	v_cvt_pk_f16_f32 v175, v58, v59
	s_nop 1
	v_permlane16_swap_b32_e32 v172, v174
	v_permlane16_swap_b32_e32 v173, v175
	global_store_dwordx4 v177, v[172:175], s[80:81] nt
	v_cvt_pk_f16_f32 v228, v60, v61
	v_cvt_pk_f16_f32 v229, v62, v63
	v_cvt_pk_f16_f32 v230, v64, v65
	v_cvt_pk_f16_f32 v231, v66, v67
	s_nop 1
	v_permlane16_swap_b32_e32 v228, v230
	v_permlane16_swap_b32_e32 v229, v231
	global_store_dwordx4 v177, v[228:231], s[80:81] offset:64 nt
	v_add_u32_e32 v177, 0xc000, v177
	v_cvt_pk_f16_f32 v172, v68, v69
	v_cvt_pk_f16_f32 v173, v70, v71
	v_cvt_pk_f16_f32 v174, v72, v73
	v_cvt_pk_f16_f32 v175, v74, v75
	s_nop 1
	v_permlane16_swap_b32_e32 v172, v174
	v_permlane16_swap_b32_e32 v173, v175
	global_store_dwordx4 v177, v[172:175], s[80:81] nt
	v_cvt_pk_f16_f32 v228, v76, v77
	v_cvt_pk_f16_f32 v229, v78, v79
	v_cvt_pk_f16_f32 v230, v80, v81
	v_cvt_pk_f16_f32 v231, v82, v83
	s_nop 1
	v_permlane16_swap_b32_e32 v228, v230
	v_permlane16_swap_b32_e32 v229, v231
	global_store_dwordx4 v177, v[228:231], s[80:81] offset:64 nt
	v_add_u32_e32 v177, 0xc000, v177
	v_cvt_pk_f16_f32 v172, v84, v85
	v_cvt_pk_f16_f32 v173, v86, v87
	v_cvt_pk_f16_f32 v174, v88, v89
	v_cvt_pk_f16_f32 v175, v90, v91
	s_nop 1
	v_permlane16_swap_b32_e32 v172, v174
	v_permlane16_swap_b32_e32 v173, v175
	global_store_dwordx4 v177, v[172:175], s[80:81] nt
	v_cvt_pk_f16_f32 v228, v92, v93
	v_cvt_pk_f16_f32 v229, v94, v95
	v_cvt_pk_f16_f32 v230, v96, v97
	v_cvt_pk_f16_f32 v231, v98, v99
	s_nop 1
	v_permlane16_swap_b32_e32 v228, v230
	v_permlane16_swap_b32_e32 v229, v231
	global_store_dwordx4 v177, v[228:231], s[80:81] offset:64 nt
	v_add_u32_e32 v177, 0xc000, v177
	v_cvt_pk_f16_f32 v172, v100, v101
	v_cvt_pk_f16_f32 v173, v102, v103
	v_cvt_pk_f16_f32 v174, v104, v105
	v_cvt_pk_f16_f32 v175, v106, v107
	s_nop 1
	v_permlane16_swap_b32_e32 v172, v174
	v_permlane16_swap_b32_e32 v173, v175
	global_store_dwordx4 v177, v[172:175], s[80:81] nt
	v_cvt_pk_f16_f32 v228, v108, v109
	v_cvt_pk_f16_f32 v229, v110, v111
	v_cvt_pk_f16_f32 v230, v112, v113
	v_cvt_pk_f16_f32 v231, v114, v115
	s_nop 1
	v_permlane16_swap_b32_e32 v228, v230
	v_permlane16_swap_b32_e32 v229, v231
	global_store_dwordx4 v177, v[228:231], s[80:81] offset:64 nt
	v_add_u32_e32 v177, 0xc000, v177
	v_cvt_pk_f16_f32 v172, v116, v117
	v_cvt_pk_f16_f32 v173, v118, v119
	v_cvt_pk_f16_f32 v174, v120, v121
	v_cvt_pk_f16_f32 v175, v122, v123
	s_nop 1
	v_permlane16_swap_b32_e32 v172, v174
	v_permlane16_swap_b32_e32 v173, v175
	global_store_dwordx4 v177, v[172:175], s[80:81] nt
	v_cvt_pk_f16_f32 v228, v124, v125
	v_cvt_pk_f16_f32 v229, v126, v127
	v_cvt_pk_f16_f32 v230, v128, v129
	v_cvt_pk_f16_f32 v231, v130, v131
	s_nop 1
	v_permlane16_swap_b32_e32 v228, v230
	v_permlane16_swap_b32_e32 v229, v231
	global_store_dwordx4 v177, v[228:231], s[80:81] offset:64 nt
	s_nop 1
	s_add_i32 s46, s46, s76
	s_cmp_ge_i32 s46, s59
	s_cbranch_scc1 .LBB0_1133
	s_branch .LBB0_1121
